# hand-written lru_agg and lru_apply phases: 16B coalesced loads, 8-row double-buffered batches, batched chunk-prefix loads (was load-wait-fma serialized)
# speedup vs baseline: 1.0421x; 1.0335x over previous
; DI float bflo(unsigned w) { return __uint_as_float(w << 16); }
; DI float bfhi(unsigned w) { return __uint_as_float(w & 0xffff0000u); }
; DI void chunk_info(int ch, int& row0, int& len) { if (ch < 256) { row0 = ch * 64; len = 64; } else { row0 = NP + (ch - 256) * 32; len = 32; } }
; DI void phase_lru_agg(const Frame& F) {
;     const float* A = (const float*)(F.ws + WS_A); const float* Bn = (const float*)(F.ws + WS_BN); float* AG = (float*)(F.ws + WS_AGG);
;     for (int it = F.gtid; it < 264 * DRNN; it += F.GT) { const int ch = it / DRNN, c = it % DRNN; int row0, len; chunk_info(ch, row0, len);
;         float P = 1.f, S = 0.f; const unsigned* ab = (const unsigned*)A + (size_t)row0 * DRNN + c;
; #pragma unroll 16
;         for (int t = 0; t < len; ++t) { const unsigned w = ab[(size_t)t * DRNN]; const float at = 1.f - bflo(w), bt = bfhi(w); S = at * S + bt; P *= at; }
;         AG[it] = P; AG[264 * DRNN + it] = S; }
.LBB0_1915:
	s_or_b64 exec, exec, s[0:1]
	v_readlane_b32 s0, v254, 33
	v_mov_b32_e32 v1, v220
	s_waitcnt lgkmcnt(0)
	v_mov_b32_e32 v2, s0
	s_barrier
	v_and_b32_e32 v1, 63, v220
	v_mov_b32_e32 v3, 0x23110
	ds_read_b64 v[4:5], v3
	v_lshlrev_b32_e32 v2, 3, v1
	v_lshlrev_b32_e32 v1, 4, v1
	v_readfirstlane_b32 s2, v220
	s_lshr_b32 s2, s2, 6
	v_readlane_b32 s66, v253, 2
	s_lshr_b32 s66, s66, 3
	s_mul_i32 s2, s2, s54
	s_add_i32 s2, s2, s66
	s_mov_b32 s71, 0xffff0000
	s_waitcnt lgkmcnt(0)
	v_readfirstlane_b32 s42, v4
	v_readfirstlane_b32 s43, v5
	s_cmp_ge_u32 s2, 0x528
	s_cbranch_scc1 .Llagg_done
	s_mul_i32 s66, s2, 0xcccd
	s_lshr_b32 s24, s66, 18
	s_mul_i32 s66, s24, 5
	s_sub_i32 s32, s2, s66
	s_lshl_b32 s15, s24, 6
	s_sub_i32 s66, s24, 0x100
	s_lshl_b32 s66, s66, 5
	s_add_i32 s66, s66, 0x4000
	s_cmp_lt_u32 s24, 0x100
	s_cselect_b32 s15, s15, s66
	s_cselect_b32 s41, 4, 2
	s_lshl_b32 s69, s32, 10
	v_add_u32_e32 v40, 0, v1
	v_add_u32_e32 v41, 5120, v1
	v_add_u32_e32 v42, 10240, v1
	v_add_u32_e32 v43, 15360, v1
	v_add_u32_e32 v44, 20480, v1
	v_add_u32_e32 v45, 25600, v1
	v_add_u32_e32 v46, 30720, v1
	v_add_u32_e32 v47, 35840, v1
	s_mul_i32 s66, s15, 0x1400
	s_add_i32 s66, s66, s69
	s_add_u32 s44, s42, s66
	s_addc_u32 s45, s43, 0
	s_add_u32 s44, s44, 0x16000000
	s_addc_u32 s45, s45, 0
	global_load_dwordx4 v[78:81], v40, s[44:45]
	global_load_dwordx4 v[82:85], v41, s[44:45]
	global_load_dwordx4 v[86:89], v42, s[44:45]
	global_load_dwordx4 v[90:93], v43, s[44:45]
	global_load_dwordx4 v[98:101], v44, s[44:45]
	global_load_dwordx4 v[102:105], v45, s[44:45]
	global_load_dwordx4 v[106:109], v46, s[44:45]
	global_load_dwordx4 v[140:143], v47, s[44:45]
	s_add_u32 s44, s44, 0xa000
	s_addc_u32 s45, s45, 0
	global_load_dwordx4 v[144:147], v40, s[44:45]
	global_load_dwordx4 v[148:151], v41, s[44:45]
	global_load_dwordx4 v[152:155], v42, s[44:45]
	global_load_dwordx4 v[156:159], v43, s[44:45]
	global_load_dwordx4 v[160:163], v44, s[44:45]
	global_load_dwordx4 v[164:167], v45, s[44:45]
	global_load_dwordx4 v[168:171], v46, s[44:45]
	global_load_dwordx4 v[180:183], v47, s[44:45]
	s_add_u32 s44, s44, 0xa000
	s_addc_u32 s45, s45, 0
	v_mov_b32_e32 v22, 0
	v_mov_b32_e32 v30, 1.0
	v_mov_b32_e32 v23, 0
	v_mov_b32_e32 v31, 1.0
	v_mov_b32_e32 v24, 0
	v_mov_b32_e32 v32, 1.0
	v_mov_b32_e32 v25, 0
	v_mov_b32_e32 v33, 1.0
.Llagg_loop:
	s_waitcnt vmcnt(8)
	v_lshlrev_b32_e32 v3, 16, v78
	v_and_b32_e32 v7, s71, v78
	v_lshlrev_b32_e32 v4, 16, v79
	v_and_b32_e32 v8, s71, v79
	v_lshlrev_b32_e32 v5, 16, v80
	v_and_b32_e32 v9, s71, v80
	v_lshlrev_b32_e32 v6, 16, v81
	v_and_b32_e32 v10, s71, v81
	v_sub_f32_e32 v3, 1.0, v3
	v_sub_f32_e32 v4, 1.0, v4
	v_sub_f32_e32 v5, 1.0, v5
	v_sub_f32_e32 v6, 1.0, v6
	v_fma_f32 v22, v3, v22, v7
	v_mul_f32_e32 v30, v30, v3
	v_fma_f32 v23, v4, v23, v8
	v_mul_f32_e32 v31, v31, v4
	v_fma_f32 v24, v5, v24, v9
	v_mul_f32_e32 v32, v32, v5
	v_fma_f32 v25, v6, v25, v10
	v_mul_f32_e32 v33, v33, v6
	v_lshlrev_b32_e32 v3, 16, v82
	v_and_b32_e32 v7, s71, v82
	v_lshlrev_b32_e32 v4, 16, v83
	v_and_b32_e32 v8, s71, v83
	v_lshlrev_b32_e32 v5, 16, v84
	v_and_b32_e32 v9, s71, v84
	v_lshlrev_b32_e32 v6, 16, v85
	v_and_b32_e32 v10, s71, v85
	v_sub_f32_e32 v3, 1.0, v3
	v_sub_f32_e32 v4, 1.0, v4
	v_sub_f32_e32 v5, 1.0, v5
	v_sub_f32_e32 v6, 1.0, v6
	v_fma_f32 v22, v3, v22, v7
	v_mul_f32_e32 v30, v30, v3
	v_fma_f32 v23, v4, v23, v8
	v_mul_f32_e32 v31, v31, v4
	v_fma_f32 v24, v5, v24, v9
	v_mul_f32_e32 v32, v32, v5
	v_fma_f32 v25, v6, v25, v10
	v_mul_f32_e32 v33, v33, v6
	v_lshlrev_b32_e32 v3, 16, v86
	v_and_b32_e32 v7, s71, v86
	v_lshlrev_b32_e32 v4, 16, v87
	v_and_b32_e32 v8, s71, v87
	v_lshlrev_b32_e32 v5, 16, v88
	v_and_b32_e32 v9, s71, v88
	v_lshlrev_b32_e32 v6, 16, v89
	v_and_b32_e32 v10, s71, v89
	v_sub_f32_e32 v3, 1.0, v3
	v_sub_f32_e32 v4, 1.0, v4
	v_sub_f32_e32 v5, 1.0, v5
	v_sub_f32_e32 v6, 1.0, v6
	v_fma_f32 v22, v3, v22, v7
	v_mul_f32_e32 v30, v30, v3
	v_fma_f32 v23, v4, v23, v8
	v_mul_f32_e32 v31, v31, v4
	v_fma_f32 v24, v5, v24, v9
	v_mul_f32_e32 v32, v32, v5
	v_fma_f32 v25, v6, v25, v10
	v_mul_f32_e32 v33, v33, v6
	v_lshlrev_b32_e32 v3, 16, v90
	v_and_b32_e32 v7, s71, v90
	v_lshlrev_b32_e32 v4, 16, v91
	v_and_b32_e32 v8, s71, v91
	v_lshlrev_b32_e32 v5, 16, v92
	v_and_b32_e32 v9, s71, v92
	v_lshlrev_b32_e32 v6, 16, v93
	v_and_b32_e32 v10, s71, v93
	v_sub_f32_e32 v3, 1.0, v3
	v_sub_f32_e32 v4, 1.0, v4
	v_sub_f32_e32 v5, 1.0, v5
	v_sub_f32_e32 v6, 1.0, v6
	v_fma_f32 v22, v3, v22, v7
	v_mul_f32_e32 v30, v30, v3
	v_fma_f32 v23, v4, v23, v8
	v_mul_f32_e32 v31, v31, v4
	v_fma_f32 v24, v5, v24, v9
	v_mul_f32_e32 v32, v32, v5
	v_fma_f32 v25, v6, v25, v10
	v_mul_f32_e32 v33, v33, v6
	v_lshlrev_b32_e32 v3, 16, v98
	v_and_b32_e32 v7, s71, v98
	v_lshlrev_b32_e32 v4, 16, v99
	v_and_b32_e32 v8, s71, v99
	v_lshlrev_b32_e32 v5, 16, v100
	v_and_b32_e32 v9, s71, v100
	v_lshlrev_b32_e32 v6, 16, v101
	v_and_b32_e32 v10, s71, v101
	v_sub_f32_e32 v3, 1.0, v3
	v_sub_f32_e32 v4, 1.0, v4
	v_sub_f32_e32 v5, 1.0, v5
	v_sub_f32_e32 v6, 1.0, v6
	v_fma_f32 v22, v3, v22, v7
	v_mul_f32_e32 v30, v30, v3
	v_fma_f32 v23, v4, v23, v8
	v_mul_f32_e32 v31, v31, v4
	v_fma_f32 v24, v5, v24, v9
	v_mul_f32_e32 v32, v32, v5
	v_fma_f32 v25, v6, v25, v10
	v_mul_f32_e32 v33, v33, v6
	v_lshlrev_b32_e32 v3, 16, v102
	v_and_b32_e32 v7, s71, v102
	v_lshlrev_b32_e32 v4, 16, v103
	v_and_b32_e32 v8, s71, v103
	v_lshlrev_b32_e32 v5, 16, v104
	v_and_b32_e32 v9, s71, v104
	v_lshlrev_b32_e32 v6, 16, v105
	v_and_b32_e32 v10, s71, v105
	v_sub_f32_e32 v3, 1.0, v3
	v_sub_f32_e32 v4, 1.0, v4
	v_sub_f32_e32 v5, 1.0, v5
	v_sub_f32_e32 v6, 1.0, v6
	v_fma_f32 v22, v3, v22, v7
	v_mul_f32_e32 v30, v30, v3
	v_fma_f32 v23, v4, v23, v8
	v_mul_f32_e32 v31, v31, v4
	v_fma_f32 v24, v5, v24, v9
	v_mul_f32_e32 v32, v32, v5
	v_fma_f32 v25, v6, v25, v10
	v_mul_f32_e32 v33, v33, v6
	v_lshlrev_b32_e32 v3, 16, v106
	v_and_b32_e32 v7, s71, v106
	v_lshlrev_b32_e32 v4, 16, v107
	v_and_b32_e32 v8, s71, v107
	v_lshlrev_b32_e32 v5, 16, v108
	v_and_b32_e32 v9, s71, v108
	v_lshlrev_b32_e32 v6, 16, v109
	v_and_b32_e32 v10, s71, v109
	v_sub_f32_e32 v3, 1.0, v3
	v_sub_f32_e32 v4, 1.0, v4
	v_sub_f32_e32 v5, 1.0, v5
	v_sub_f32_e32 v6, 1.0, v6
	v_fma_f32 v22, v3, v22, v7
	v_mul_f32_e32 v30, v30, v3
	v_fma_f32 v23, v4, v23, v8
	v_mul_f32_e32 v31, v31, v4
	v_fma_f32 v24, v5, v24, v9
	v_mul_f32_e32 v32, v32, v5
	v_fma_f32 v25, v6, v25, v10
	v_mul_f32_e32 v33, v33, v6
	v_lshlrev_b32_e32 v3, 16, v140
	v_and_b32_e32 v7, s71, v140
	v_lshlrev_b32_e32 v4, 16, v141
	v_and_b32_e32 v8, s71, v141
	v_lshlrev_b32_e32 v5, 16, v142
	v_and_b32_e32 v9, s71, v142
	v_lshlrev_b32_e32 v6, 16, v143
	v_and_b32_e32 v10, s71, v143
	v_sub_f32_e32 v3, 1.0, v3
	v_sub_f32_e32 v4, 1.0, v4
	v_sub_f32_e32 v5, 1.0, v5
	v_sub_f32_e32 v6, 1.0, v6
	v_fma_f32 v22, v3, v22, v7
	v_mul_f32_e32 v30, v30, v3
	v_fma_f32 v23, v4, v23, v8
	v_mul_f32_e32 v31, v31, v4
	v_fma_f32 v24, v5, v24, v9
	v_mul_f32_e32 v32, v32, v5
	v_fma_f32 v25, v6, v25, v10
	v_mul_f32_e32 v33, v33, v6
	s_cmp_le_u32 s41, 1
	s_cbranch_scc1 .Llagg_last
; DI float bflo(unsigned w) { return __uint_as_float(w << 16); }
; DI float bfhi(unsigned w) { return __uint_as_float(w & 0xffff0000u); }
; DI void chunk_info(int ch, int& row0, int& len) { if (ch < 256) { row0 = ch * 64; len = 64; } else { row0 = NP + (ch - 256) * 32; len = 32; } }
; DI void phase_lru_agg(const Frame& F) {
;     ...
;     for (int it = F.gtid; it < 264 * DRNN; it += F.GT) { const int ch = it / DRNN, c = it % DRNN; int row0, len; chunk_info(ch, row0, len);
;         float P = 1.f, S = 0.f; const unsigned* ab = (const unsigned*)A + (size_t)row0 * DRNN + c;
; #pragma unroll 16
;         for (int t = 0; t < len; ++t) { const unsigned w = ab[(size_t)t * DRNN]; const float at = 1.f - bflo(w), bt = bfhi(w); S = at * S + bt; P *= at; }
	global_load_dwordx4 v[78:81], v40, s[44:45]
	global_load_dwordx4 v[82:85], v41, s[44:45]
	global_load_dwordx4 v[86:89], v42, s[44:45]
	global_load_dwordx4 v[90:93], v43, s[44:45]
	global_load_dwordx4 v[98:101], v44, s[44:45]
	global_load_dwordx4 v[102:105], v45, s[44:45]
	global_load_dwordx4 v[106:109], v46, s[44:45]
	global_load_dwordx4 v[140:143], v47, s[44:45]
	s_add_u32 s44, s44, 0xa000
	s_addc_u32 s45, s45, 0
	s_waitcnt vmcnt(8)
	v_lshlrev_b32_e32 v3, 16, v144
	v_and_b32_e32 v7, s71, v144
	v_lshlrev_b32_e32 v4, 16, v145
	v_and_b32_e32 v8, s71, v145
	v_lshlrev_b32_e32 v5, 16, v146
	v_and_b32_e32 v9, s71, v146
	v_lshlrev_b32_e32 v6, 16, v147
	v_and_b32_e32 v10, s71, v147
	v_sub_f32_e32 v3, 1.0, v3
	v_sub_f32_e32 v4, 1.0, v4
	v_sub_f32_e32 v5, 1.0, v5
	v_sub_f32_e32 v6, 1.0, v6
	v_fma_f32 v22, v3, v22, v7
	v_mul_f32_e32 v30, v30, v3
	v_fma_f32 v23, v4, v23, v8
	v_mul_f32_e32 v31, v31, v4
	v_fma_f32 v24, v5, v24, v9
	v_mul_f32_e32 v32, v32, v5
	v_fma_f32 v25, v6, v25, v10
	v_mul_f32_e32 v33, v33, v6
	v_lshlrev_b32_e32 v3, 16, v148
	v_and_b32_e32 v7, s71, v148
	v_lshlrev_b32_e32 v4, 16, v149
	v_and_b32_e32 v8, s71, v149
	v_lshlrev_b32_e32 v5, 16, v150
	v_and_b32_e32 v9, s71, v150
	v_lshlrev_b32_e32 v6, 16, v151
	v_and_b32_e32 v10, s71, v151
	v_sub_f32_e32 v3, 1.0, v3
	v_sub_f32_e32 v4, 1.0, v4
	v_sub_f32_e32 v5, 1.0, v5
	v_sub_f32_e32 v6, 1.0, v6
	v_fma_f32 v22, v3, v22, v7
	v_mul_f32_e32 v30, v30, v3
	v_fma_f32 v23, v4, v23, v8
	v_mul_f32_e32 v31, v31, v4
	v_fma_f32 v24, v5, v24, v9
	v_mul_f32_e32 v32, v32, v5
	v_fma_f32 v25, v6, v25, v10
	v_mul_f32_e32 v33, v33, v6
	v_lshlrev_b32_e32 v3, 16, v152
	v_and_b32_e32 v7, s71, v152
	v_lshlrev_b32_e32 v4, 16, v153
	v_and_b32_e32 v8, s71, v153
	v_lshlrev_b32_e32 v5, 16, v154
	v_and_b32_e32 v9, s71, v154
	v_lshlrev_b32_e32 v6, 16, v155
	v_and_b32_e32 v10, s71, v155
	v_sub_f32_e32 v3, 1.0, v3
	v_sub_f32_e32 v4, 1.0, v4
	v_sub_f32_e32 v5, 1.0, v5
	v_sub_f32_e32 v6, 1.0, v6
	v_fma_f32 v22, v3, v22, v7
	v_mul_f32_e32 v30, v30, v3
	v_fma_f32 v23, v4, v23, v8
	v_mul_f32_e32 v31, v31, v4
	v_fma_f32 v24, v5, v24, v9
	v_mul_f32_e32 v32, v32, v5
	v_fma_f32 v25, v6, v25, v10
	v_mul_f32_e32 v33, v33, v6
	v_lshlrev_b32_e32 v3, 16, v156
	v_and_b32_e32 v7, s71, v156
	v_lshlrev_b32_e32 v4, 16, v157
	v_and_b32_e32 v8, s71, v157
	v_lshlrev_b32_e32 v5, 16, v158
	v_and_b32_e32 v9, s71, v158
	v_lshlrev_b32_e32 v6, 16, v159
	v_and_b32_e32 v10, s71, v159
	v_sub_f32_e32 v3, 1.0, v3
	v_sub_f32_e32 v4, 1.0, v4
	v_sub_f32_e32 v5, 1.0, v5
	v_sub_f32_e32 v6, 1.0, v6
	v_fma_f32 v22, v3, v22, v7
	v_mul_f32_e32 v30, v30, v3
	v_fma_f32 v23, v4, v23, v8
	v_mul_f32_e32 v31, v31, v4
	v_fma_f32 v24, v5, v24, v9
	v_mul_f32_e32 v32, v32, v5
	v_fma_f32 v25, v6, v25, v10
	v_mul_f32_e32 v33, v33, v6
	v_lshlrev_b32_e32 v3, 16, v160
	v_and_b32_e32 v7, s71, v160
	v_lshlrev_b32_e32 v4, 16, v161
	v_and_b32_e32 v8, s71, v161
	v_lshlrev_b32_e32 v5, 16, v162
	v_and_b32_e32 v9, s71, v162
	v_lshlrev_b32_e32 v6, 16, v163
	v_and_b32_e32 v10, s71, v163
	v_sub_f32_e32 v3, 1.0, v3
	v_sub_f32_e32 v4, 1.0, v4
	v_sub_f32_e32 v5, 1.0, v5
	v_sub_f32_e32 v6, 1.0, v6
	v_fma_f32 v22, v3, v22, v7
	v_mul_f32_e32 v30, v30, v3
	v_fma_f32 v23, v4, v23, v8
	v_mul_f32_e32 v31, v31, v4
	v_fma_f32 v24, v5, v24, v9
	v_mul_f32_e32 v32, v32, v5
	v_fma_f32 v25, v6, v25, v10
	v_mul_f32_e32 v33, v33, v6
	v_lshlrev_b32_e32 v3, 16, v164
	v_and_b32_e32 v7, s71, v164
	v_lshlrev_b32_e32 v4, 16, v165
	v_and_b32_e32 v8, s71, v165
	v_lshlrev_b32_e32 v5, 16, v166
	v_and_b32_e32 v9, s71, v166
	v_lshlrev_b32_e32 v6, 16, v167
	v_and_b32_e32 v10, s71, v167
	v_sub_f32_e32 v3, 1.0, v3
	v_sub_f32_e32 v4, 1.0, v4
	v_sub_f32_e32 v5, 1.0, v5
	v_sub_f32_e32 v6, 1.0, v6
	v_fma_f32 v22, v3, v22, v7
	v_mul_f32_e32 v30, v30, v3
	v_fma_f32 v23, v4, v23, v8
	v_mul_f32_e32 v31, v31, v4
	v_fma_f32 v24, v5, v24, v9
	v_mul_f32_e32 v32, v32, v5
	v_fma_f32 v25, v6, v25, v10
	v_mul_f32_e32 v33, v33, v6
	v_lshlrev_b32_e32 v3, 16, v168
	v_and_b32_e32 v7, s71, v168
	v_lshlrev_b32_e32 v4, 16, v169
	v_and_b32_e32 v8, s71, v169
	v_lshlrev_b32_e32 v5, 16, v170
	v_and_b32_e32 v9, s71, v170
	v_lshlrev_b32_e32 v6, 16, v171
	v_and_b32_e32 v10, s71, v171
	v_sub_f32_e32 v3, 1.0, v3
	v_sub_f32_e32 v4, 1.0, v4
	v_sub_f32_e32 v5, 1.0, v5
	v_sub_f32_e32 v6, 1.0, v6
	v_fma_f32 v22, v3, v22, v7
	v_mul_f32_e32 v30, v30, v3
	v_fma_f32 v23, v4, v23, v8
	v_mul_f32_e32 v31, v31, v4
	v_fma_f32 v24, v5, v24, v9
	v_mul_f32_e32 v32, v32, v5
	v_fma_f32 v25, v6, v25, v10
	v_mul_f32_e32 v33, v33, v6
	v_lshlrev_b32_e32 v3, 16, v180
	v_and_b32_e32 v7, s71, v180
	v_lshlrev_b32_e32 v4, 16, v181
	v_and_b32_e32 v8, s71, v181
	v_lshlrev_b32_e32 v5, 16, v182
	v_and_b32_e32 v9, s71, v182
	v_lshlrev_b32_e32 v6, 16, v183
	v_and_b32_e32 v10, s71, v183
	v_sub_f32_e32 v3, 1.0, v3
	v_sub_f32_e32 v4, 1.0, v4
	v_sub_f32_e32 v5, 1.0, v5
	v_sub_f32_e32 v6, 1.0, v6
	v_fma_f32 v22, v3, v22, v7
	v_mul_f32_e32 v30, v30, v3
	v_fma_f32 v23, v4, v23, v8
	v_mul_f32_e32 v31, v31, v4
	v_fma_f32 v24, v5, v24, v9
	v_mul_f32_e32 v32, v32, v5
	v_fma_f32 v25, v6, v25, v10
	v_mul_f32_e32 v33, v33, v6
	global_load_dwordx4 v[144:147], v40, s[44:45]
	global_load_dwordx4 v[148:151], v41, s[44:45]
	global_load_dwordx4 v[152:155], v42, s[44:45]
	global_load_dwordx4 v[156:159], v43, s[44:45]
	global_load_dwordx4 v[160:163], v44, s[44:45]
	global_load_dwordx4 v[164:167], v45, s[44:45]
	global_load_dwordx4 v[168:171], v46, s[44:45]
	global_load_dwordx4 v[180:183], v47, s[44:45]
	s_add_u32 s44, s44, 0xa000
	s_addc_u32 s45, s45, 0
	s_sub_i32 s41, s41, 1
	s_branch .Llagg_loop
; DI float bflo(unsigned w) { return __uint_as_float(w << 16); }
; DI float bfhi(unsigned w) { return __uint_as_float(w & 0xffff0000u); }
; DI void chunk_info(int ch, int& row0, int& len) { if (ch < 256) { row0 = ch * 64; len = 64; } else { row0 = NP + (ch - 256) * 32; len = 32; } }
; DI void phase_lru_agg(const Frame& F) {
;     ...
;     for (int it = F.gtid; it < 264 * DRNN; it += F.GT) { const int ch = it / DRNN, c = it % DRNN; int row0, len; chunk_info(ch, row0, len);
;         float P = 1.f, S = 0.f; const unsigned* ab = (const unsigned*)A + (size_t)row0 * DRNN + c;
; #pragma unroll 16
;         for (int t = 0; t < len; ++t) { const unsigned w = ab[(size_t)t * DRNN]; const float at = 1.f - bflo(w), bt = bfhi(w); S = at * S + bt; P *= at; }
;         AG[it] = P; AG[264 * DRNN + it] = S; }
.Llagg_last:
	s_waitcnt vmcnt(0)
	v_lshlrev_b32_e32 v3, 16, v144
	v_and_b32_e32 v7, s71, v144
	v_lshlrev_b32_e32 v4, 16, v145
	v_and_b32_e32 v8, s71, v145
	v_lshlrev_b32_e32 v5, 16, v146
	v_and_b32_e32 v9, s71, v146
	v_lshlrev_b32_e32 v6, 16, v147
	v_and_b32_e32 v10, s71, v147
	v_sub_f32_e32 v3, 1.0, v3
	v_sub_f32_e32 v4, 1.0, v4
	v_sub_f32_e32 v5, 1.0, v5
	v_sub_f32_e32 v6, 1.0, v6
	v_fma_f32 v22, v3, v22, v7
	v_mul_f32_e32 v30, v30, v3
	v_fma_f32 v23, v4, v23, v8
	v_mul_f32_e32 v31, v31, v4
	v_fma_f32 v24, v5, v24, v9
	v_mul_f32_e32 v32, v32, v5
	v_fma_f32 v25, v6, v25, v10
	v_mul_f32_e32 v33, v33, v6
	v_lshlrev_b32_e32 v3, 16, v148
	v_and_b32_e32 v7, s71, v148
	v_lshlrev_b32_e32 v4, 16, v149
	v_and_b32_e32 v8, s71, v149
	v_lshlrev_b32_e32 v5, 16, v150
	v_and_b32_e32 v9, s71, v150
	v_lshlrev_b32_e32 v6, 16, v151
	v_and_b32_e32 v10, s71, v151
	v_sub_f32_e32 v3, 1.0, v3
	v_sub_f32_e32 v4, 1.0, v4
	v_sub_f32_e32 v5, 1.0, v5
	v_sub_f32_e32 v6, 1.0, v6
	v_fma_f32 v22, v3, v22, v7
	v_mul_f32_e32 v30, v30, v3
	v_fma_f32 v23, v4, v23, v8
	v_mul_f32_e32 v31, v31, v4
	v_fma_f32 v24, v5, v24, v9
	v_mul_f32_e32 v32, v32, v5
	v_fma_f32 v25, v6, v25, v10
	v_mul_f32_e32 v33, v33, v6
	v_lshlrev_b32_e32 v3, 16, v152
	v_and_b32_e32 v7, s71, v152
	v_lshlrev_b32_e32 v4, 16, v153
	v_and_b32_e32 v8, s71, v153
	v_lshlrev_b32_e32 v5, 16, v154
	v_and_b32_e32 v9, s71, v154
	v_lshlrev_b32_e32 v6, 16, v155
	v_and_b32_e32 v10, s71, v155
	v_sub_f32_e32 v3, 1.0, v3
	v_sub_f32_e32 v4, 1.0, v4
	v_sub_f32_e32 v5, 1.0, v5
	v_sub_f32_e32 v6, 1.0, v6
	v_fma_f32 v22, v3, v22, v7
	v_mul_f32_e32 v30, v30, v3
	v_fma_f32 v23, v4, v23, v8
	v_mul_f32_e32 v31, v31, v4
	v_fma_f32 v24, v5, v24, v9
	v_mul_f32_e32 v32, v32, v5
	v_fma_f32 v25, v6, v25, v10
	v_mul_f32_e32 v33, v33, v6
	v_lshlrev_b32_e32 v3, 16, v156
	v_and_b32_e32 v7, s71, v156
	v_lshlrev_b32_e32 v4, 16, v157
	v_and_b32_e32 v8, s71, v157
	v_lshlrev_b32_e32 v5, 16, v158
	v_and_b32_e32 v9, s71, v158
	v_lshlrev_b32_e32 v6, 16, v159
	v_and_b32_e32 v10, s71, v159
	v_sub_f32_e32 v3, 1.0, v3
	v_sub_f32_e32 v4, 1.0, v4
	v_sub_f32_e32 v5, 1.0, v5
	v_sub_f32_e32 v6, 1.0, v6
	v_fma_f32 v22, v3, v22, v7
	v_mul_f32_e32 v30, v30, v3
	v_fma_f32 v23, v4, v23, v8
	v_mul_f32_e32 v31, v31, v4
	v_fma_f32 v24, v5, v24, v9
	v_mul_f32_e32 v32, v32, v5
	v_fma_f32 v25, v6, v25, v10
	v_mul_f32_e32 v33, v33, v6
	v_lshlrev_b32_e32 v3, 16, v160
	v_and_b32_e32 v7, s71, v160
	v_lshlrev_b32_e32 v4, 16, v161
	v_and_b32_e32 v8, s71, v161
	v_lshlrev_b32_e32 v5, 16, v162
	v_and_b32_e32 v9, s71, v162
	v_lshlrev_b32_e32 v6, 16, v163
	v_and_b32_e32 v10, s71, v163
	v_sub_f32_e32 v3, 1.0, v3
	v_sub_f32_e32 v4, 1.0, v4
	v_sub_f32_e32 v5, 1.0, v5
	v_sub_f32_e32 v6, 1.0, v6
	v_fma_f32 v22, v3, v22, v7
	v_mul_f32_e32 v30, v30, v3
	v_fma_f32 v23, v4, v23, v8
	v_mul_f32_e32 v31, v31, v4
	v_fma_f32 v24, v5, v24, v9
	v_mul_f32_e32 v32, v32, v5
	v_fma_f32 v25, v6, v25, v10
	v_mul_f32_e32 v33, v33, v6
	v_lshlrev_b32_e32 v3, 16, v164
	v_and_b32_e32 v7, s71, v164
	v_lshlrev_b32_e32 v4, 16, v165
	v_and_b32_e32 v8, s71, v165
	v_lshlrev_b32_e32 v5, 16, v166
	v_and_b32_e32 v9, s71, v166
	v_lshlrev_b32_e32 v6, 16, v167
	v_and_b32_e32 v10, s71, v167
	v_sub_f32_e32 v3, 1.0, v3
	v_sub_f32_e32 v4, 1.0, v4
	v_sub_f32_e32 v5, 1.0, v5
	v_sub_f32_e32 v6, 1.0, v6
	v_fma_f32 v22, v3, v22, v7
	v_mul_f32_e32 v30, v30, v3
	v_fma_f32 v23, v4, v23, v8
	v_mul_f32_e32 v31, v31, v4
	v_fma_f32 v24, v5, v24, v9
	v_mul_f32_e32 v32, v32, v5
	v_fma_f32 v25, v6, v25, v10
	v_mul_f32_e32 v33, v33, v6
	v_lshlrev_b32_e32 v3, 16, v168
	v_and_b32_e32 v7, s71, v168
	v_lshlrev_b32_e32 v4, 16, v169
	v_and_b32_e32 v8, s71, v169
	v_lshlrev_b32_e32 v5, 16, v170
	v_and_b32_e32 v9, s71, v170
	v_lshlrev_b32_e32 v6, 16, v171
	v_and_b32_e32 v10, s71, v171
	v_sub_f32_e32 v3, 1.0, v3
	v_sub_f32_e32 v4, 1.0, v4
	v_sub_f32_e32 v5, 1.0, v5
	v_sub_f32_e32 v6, 1.0, v6
	v_fma_f32 v22, v3, v22, v7
	v_mul_f32_e32 v30, v30, v3
	v_fma_f32 v23, v4, v23, v8
	v_mul_f32_e32 v31, v31, v4
	v_fma_f32 v24, v5, v24, v9
	v_mul_f32_e32 v32, v32, v5
	v_fma_f32 v25, v6, v25, v10
	v_mul_f32_e32 v33, v33, v6
	v_lshlrev_b32_e32 v3, 16, v180
	v_and_b32_e32 v7, s71, v180
	v_lshlrev_b32_e32 v4, 16, v181
	v_and_b32_e32 v8, s71, v181
	v_lshlrev_b32_e32 v5, 16, v182
	v_and_b32_e32 v9, s71, v182
	v_lshlrev_b32_e32 v6, 16, v183
	v_and_b32_e32 v10, s71, v183
	v_sub_f32_e32 v3, 1.0, v3
	v_sub_f32_e32 v4, 1.0, v4
	v_sub_f32_e32 v5, 1.0, v5
	v_sub_f32_e32 v6, 1.0, v6
	v_fma_f32 v22, v3, v22, v7
	v_mul_f32_e32 v30, v30, v3
	v_fma_f32 v23, v4, v23, v8
	v_mul_f32_e32 v31, v31, v4
	v_fma_f32 v24, v5, v24, v9
	v_mul_f32_e32 v32, v32, v5
	v_fma_f32 v25, v6, v25, v10
	v_mul_f32_e32 v33, v33, v6
	s_mul_i32 s66, s24, 0x1400
	s_add_i32 s66, s66, s69
	s_add_i32 s66, s66, 0x400000
	s_add_u32 s78, s42, s66
	s_addc_u32 s79, s43, 0
	global_store_dwordx4 v1, v[30:33], s[78:79]
	s_add_u32 s78, s78, 0x14a000
	s_addc_u32 s79, s79, 0
	global_store_dwordx4 v1, v[22:25], s[78:79]
.Llagg_done:
.LBB0_1920:
	s_or_b64 exec, exec, s[0:1]
	s_waitcnt vmcnt(0)
	s_waitcnt lgkmcnt(0)
	s_barrier
	s_mov_b64 s[0:1], exec
	v_readlane_b32 s18, v253, 0
	v_readlane_b32 s19, v253, 1
	s_and_b64 s[18:19], s[0:1], s[18:19]
	s_mov_b64 exec, s[18:19]
	s_cbranch_execz .LBB0_1964
	v_readlane_b32 s2, v254, 47
	s_waitcnt vmcnt(0) expcnt(0) lgkmcnt(0)
	s_nop 0
	v_mov_b32_e32 v1, s2
	ds_read_b32 v4, v1
	v_readlane_b32 s2, v254, 48
	s_waitcnt lgkmcnt(0)
	v_cmp_ne_u32_e32 vcc, 0, v4
	v_mov_b32_e32 v1, s2
	ds_read_b32 v2, v1
	s_cbranch_vccnz .LBB0_1935
	s_mov_b32 s2, 1
	s_mov_b64 s[18:19], 0
	s_branch .LBB0_1925

; DI void chunk_info(int ch, int& row0, int& len) { if (ch < 256) { row0 = ch * 64; len = 64; } else { row0 = NP + (ch - 256) * 32; len = 32; } }
; DI void phase_lru_apply(const Frame& F, int j) {
;     ...
;     for (int it = F.gtid; it < 264 * DRNN; it += F.GT) { const int ch = it / DRNN, c = it % DRNN; int row0, len; chunk_info(ch, row0, len);
;         float h; int f0; bool lastc; float* ho;
;         if (ch < 256) { f0 = ch & ~127; h = 0.f; lastc = (ch & 127) == 127; ho = F.out + O_HP + ((size_t)j * 2 + (ch >> 7)) * DRNN + c; }
;         else { f0 = ch; h = F.in[4][((size_t)j * 8 + (ch - 256)) * DRNN + c]; lastc = true; ho = F.out + O_HS + ((size_t)j * 8 + (ch - 256)) * DRNN + c; }
; #pragma unroll 8
;         for (int cc = f0; cc < ch; ++cc) h = AG[cc * DRNN + c] * h + AG[264 * DRNN + cc * DRNN + c];
.LBB0_1964:
	s_or_b64 exec, exec, s[0:1]
	v_mov_b32_e32 v1, v220
	v_readlane_b32 s0, v253, 3
	s_waitcnt lgkmcnt(0)
	s_barrier
	v_and_b32_e32 v1, 63, v220
	v_mov_b32_e32 v3, 0x23110
	ds_read_b64 v[4:5], v3
	v_lshlrev_b32_e32 v2, 3, v1
	v_lshlrev_b32_e32 v1, 4, v1
	v_readfirstlane_b32 s2, v220
	s_lshr_b32 s2, s2, 6
	v_readlane_b32 s66, v253, 2
	s_lshr_b32 s66, s66, 3
	s_mul_i32 s2, s2, s54
	s_add_i32 s2, s2, s66
	s_mov_b32 s71, 0xffff0000
	s_waitcnt lgkmcnt(0)
	v_readfirstlane_b32 s42, v4
	v_readfirstlane_b32 s43, v5
	s_cmp_ge_u32 s2, 0x528
	s_cbranch_scc1 .Llapp_done
	s_mul_i32 s66, s2, 0xcccd
	s_lshr_b32 s24, s66, 18
	s_mul_i32 s66, s24, 5
	s_sub_i32 s32, s2, s66
	s_lshl_b32 s15, s24, 6
	s_sub_i32 s66, s24, 0x100
	s_lshl_b32 s66, s66, 5
	s_add_i32 s66, s66, 0x4000
	s_cmp_lt_u32 s24, 0x100
	s_cselect_b32 s15, s15, s66
	s_cselect_b32 s41, 4, 2
	s_lshl_b32 s69, s32, 10
	v_add_u32_e32 v40, 0, v1
	v_add_u32_e32 v41, 5120, v1
	v_add_u32_e32 v42, 10240, v1
	v_add_u32_e32 v43, 15360, v1
	v_add_u32_e32 v44, 20480, v1
	v_add_u32_e32 v45, 25600, v1
	v_add_u32_e32 v46, 30720, v1
	v_add_u32_e32 v47, 35840, v1
	v_add_u32_e32 v48, 0, v2
	v_add_u32_e32 v49, 2560, v2
	v_add_u32_e32 v50, 5120, v2
	v_add_u32_e32 v51, 7680, v2
	v_add_u32_e32 v52, 10240, v2
	v_add_u32_e32 v53, 12800, v2
	v_add_u32_e32 v54, 15360, v2
	v_add_u32_e32 v55, 17920, v2
	v_readlane_b32 s75, v255, 24
	s_lshr_b32 s75, s75, 1
	v_mov_b32_e32 v3, 0x23108
	ds_read_b64 v[4:5], v3
	v_mov_b32_e32 v3, 0x23020
	ds_read_b64 v[6:7], v3
	s_mul_i32 s66, s15, 0x1400
	s_add_i32 s66, s66, s69
	s_add_u32 s44, s42, s66
	s_addc_u32 s45, s43, 0
	s_add_u32 s44, s44, 0x16000000
	s_addc_u32 s45, s45, 0
	s_mul_i32 s66, s15, 0xa00
	s_lshl_b32 s85, s32, 9
	s_add_i32 s66, s66, s85
	s_add_u32 s46, s42, s66
	s_addc_u32 s47, s43, 0
	s_add_u32 s48, s46, 0x13000000
	s_addc_u32 s49, s47, 0
	s_add_u32 s46, s46, 0x10600000
	s_addc_u32 s47, s47, 0
	s_waitcnt lgkmcnt(0)
	v_readfirstlane_b32 s92, v4
	v_readfirstlane_b32 s93, v5
	v_readfirstlane_b32 s18, v6
	v_readfirstlane_b32 s19, v7
	v_mov_b32_e32 v22, 0
	v_mov_b32_e32 v23, 0
	v_mov_b32_e32 v24, 0
	v_mov_b32_e32 v25, 0
	s_cmp_lt_u32 s24, 0x100
	s_cbranch_scc1 .Llapp_prompt
	s_lshl_b32 s66, s75, 3
	s_add_i32 s66, s66, s24
	s_sub_i32 s66, s66, 0x100
	s_mul_i32 s66, s66, 0x1400
	s_add_i32 s66, s66, s69
	s_add_u32 s90, s18, s66
	s_addc_u32 s91, s19, 0
	global_load_dwordx4 v[22:25], v1, s[90:91]
	s_add_u32 s92, s92, s66
	s_addc_u32 s93, s93, 0
	s_add_u32 s92, s92, 0x4105000
	s_addc_u32 s93, s93, 0
	s_mov_b32 s22, 1
	s_waitcnt vmcnt(0)
	s_branch .Llapp_main
.Llapp_prompt:
	s_and_b32 s23, s24, 0x7f
	s_cmp_eq_u32 s23, 0x7f
	s_cselect_b32 s22, 1, 0
	s_lshl_b32 s66, s75, 1
	s_lshr_b32 s85, s24, 7
	s_add_i32 s66, s66, s85
	s_mul_i32 s66, s66, 0x1400
	s_add_i32 s66, s66, s69
	s_add_u32 s92, s92, s66
	s_addc_u32 s93, s93, 0
	s_add_u32 s92, s92, 0x4100000
	s_addc_u32 s93, s93, 0
	s_andn2_b32 s66, s24, 0x7f
	s_mul_i32 s66, s66, 0x1400
	s_add_i32 s66, s66, s69
	s_add_i32 s66, s66, 0x400000
	s_add_u32 s78, s42, s66
	s_addc_u32 s79, s43, 0
	s_add_u32 s90, s78, 0x14a000
	s_addc_u32 s91, s79, 0
	s_mov_b32 s98, 0
.Llapp_pfx_loop:
	s_cmp_ge_u32 s98, s23
	s_cbranch_scc1 .Llapp_main
	global_load_dwordx4 v[78:81], v40, s[78:79]
	global_load_dwordx4 v[144:147], v40, s[90:91]
	s_add_i32 s66, s98, 1
	s_cmp_ge_u32 s66, s23
	s_cbranch_scc1 .Llapp_pfx_issued
	global_load_dwordx4 v[82:85], v41, s[78:79]
	global_load_dwordx4 v[148:151], v41, s[90:91]
	s_add_i32 s66, s98, 2
	s_cmp_ge_u32 s66, s23
	s_cbranch_scc1 .Llapp_pfx_issued
	global_load_dwordx4 v[86:89], v42, s[78:79]
	global_load_dwordx4 v[152:155], v42, s[90:91]
	s_add_i32 s66, s98, 3
	s_cmp_ge_u32 s66, s23
	s_cbranch_scc1 .Llapp_pfx_issued
	global_load_dwordx4 v[90:93], v43, s[78:79]
	global_load_dwordx4 v[156:159], v43, s[90:91]
	s_add_i32 s66, s98, 4
	s_cmp_ge_u32 s66, s23
	s_cbranch_scc1 .Llapp_pfx_issued
	global_load_dwordx4 v[98:101], v44, s[78:79]
	global_load_dwordx4 v[160:163], v44, s[90:91]
	s_add_i32 s66, s98, 5
	s_cmp_ge_u32 s66, s23
	s_cbranch_scc1 .Llapp_pfx_issued
	global_load_dwordx4 v[102:105], v45, s[78:79]
	global_load_dwordx4 v[164:167], v45, s[90:91]
	s_add_i32 s66, s98, 6
	s_cmp_ge_u32 s66, s23
	s_cbranch_scc1 .Llapp_pfx_issued
	global_load_dwordx4 v[106:109], v46, s[78:79]
	global_load_dwordx4 v[168:171], v46, s[90:91]
	s_add_i32 s66, s98, 7
	s_cmp_ge_u32 s66, s23
	s_cbranch_scc1 .Llapp_pfx_issued
	global_load_dwordx4 v[140:143], v47, s[78:79]
	global_load_dwordx4 v[180:183], v47, s[90:91]
.Llapp_pfx_issued:
	s_add_u32 s78, s78, 0xa000
	s_addc_u32 s79, s79, 0
	s_add_u32 s90, s90, 0xa000
	s_addc_u32 s91, s91, 0
	s_waitcnt vmcnt(0)
	v_fma_f32 v22, v78, v22, v144
	v_fma_f32 v23, v79, v23, v145
	v_fma_f32 v24, v80, v24, v146
	v_fma_f32 v25, v81, v25, v147
	s_add_i32 s66, s98, 1
	s_cmp_ge_u32 s66, s23
	s_cbranch_scc1 .Llapp_pfx_done8
	v_fma_f32 v22, v82, v22, v148
	v_fma_f32 v23, v83, v23, v149
	v_fma_f32 v24, v84, v24, v150
	v_fma_f32 v25, v85, v25, v151
	s_add_i32 s66, s98, 2
	s_cmp_ge_u32 s66, s23
	s_cbranch_scc1 .Llapp_pfx_done8
	v_fma_f32 v22, v86, v22, v152
	v_fma_f32 v23, v87, v23, v153
	v_fma_f32 v24, v88, v24, v154
	v_fma_f32 v25, v89, v25, v155
	s_add_i32 s66, s98, 3
	s_cmp_ge_u32 s66, s23
	s_cbranch_scc1 .Llapp_pfx_done8
	v_fma_f32 v22, v90, v22, v156
	v_fma_f32 v23, v91, v23, v157
	v_fma_f32 v24, v92, v24, v158
	v_fma_f32 v25, v93, v25, v159
	s_add_i32 s66, s98, 4
	s_cmp_ge_u32 s66, s23
	s_cbranch_scc1 .Llapp_pfx_done8
	v_fma_f32 v22, v98, v22, v160
	v_fma_f32 v23, v99, v23, v161
	v_fma_f32 v24, v100, v24, v162
	v_fma_f32 v25, v101, v25, v163
	s_add_i32 s66, s98, 5
	s_cmp_ge_u32 s66, s23
	s_cbranch_scc1 .Llapp_pfx_done8
	v_fma_f32 v22, v102, v22, v164
	v_fma_f32 v23, v103, v23, v165
	v_fma_f32 v24, v104, v24, v166
	v_fma_f32 v25, v105, v25, v167
	s_add_i32 s66, s98, 6
	s_cmp_ge_u32 s66, s23
	s_cbranch_scc1 .Llapp_pfx_done8
	v_fma_f32 v22, v106, v22, v168
	v_fma_f32 v23, v107, v23, v169
	v_fma_f32 v24, v108, v24, v170
	v_fma_f32 v25, v109, v25, v171
	s_add_i32 s66, s98, 7
	s_cmp_ge_u32 s66, s23
	s_cbranch_scc1 .Llapp_pfx_done8
	v_fma_f32 v22, v140, v22, v180
	v_fma_f32 v23, v141, v23, v181
	v_fma_f32 v24, v142, v24, v182
	v_fma_f32 v25, v143, v25, v183
; DI unsigned cvt_pk_bf16(float lo, float hi) { unsigned r; asm volatile("v_cvt_pk_bf16_f32 %0, %1, %2" : "=v"(r) : "v"(lo), "v"(hi)); return r; }
; DI float bf2f(unsigned short b) { return __uint_as_float(((unsigned)b) << 16); }
; DI float bflo(unsigned w) { return __uint_as_float(w << 16); }
; DI float bfhi(unsigned w) { return __uint_as_float(w & 0xffff0000u); }
; DI void phase_lru_apply(const Frame& F, int j) {
;     ...
;         for (int cc = f0; cc < ch; ++cc) h = AG[cc * DRNN + c] * h + AG[264 * DRNN + cc * DRNN + c];
;         const unsigned* ab = (const unsigned*)A + (size_t)row0 * DRNN + c; const bf16_t* gp = GB + (size_t)row0 * DRNN + c; bf16_t* hp = HG + (size_t)row0 * DRNN + c;
;         unsigned wv[2][16]; bf16_t gv[2][16];
; #pragma unroll
;         for (int i = 0; i < 16; ++i) { wv[0][i] = ab[(size_t)i * DRNN]; gv[0][i] = gp[(size_t)i * DRNN]; }
; #pragma unroll
;         for (int blk = 0; blk < 4; ++blk) { const int t0 = 16 * blk, cur = blk & 1;
;             if (t0 < len) {
;                 if (t0 + 16 < len) {
; #pragma unroll
;                     for (int i = 0; i < 16; ++i) { wv[cur ^ 1][i] = ab[(size_t)(t0 + 16 + i) * DRNN]; gv[cur ^ 1][i] = gp[(size_t)(t0 + 16 + i) * DRNN]; } }
; #pragma unroll
;                 for (int i = 0; i < 16; ++i) { h = (1.f - bflo(wv[cur][i])) * h + bfhi(wv[cur][i]); hp[(size_t)(t0 + i) * DRNN] = (bf16_t)(cvt_pk_bf16(bf2f(gv[cur][i]) * h, 0.f) & 0xffffu); } } }
.Llapp_pfx_done8:
	s_add_i32 s98, s98, 8
	s_branch .Llapp_pfx_loop
.Llapp_main:
	global_load_dwordx4 v[78:81], v40, s[44:45]
	global_load_dwordx4 v[82:85], v41, s[44:45]
	global_load_dwordx4 v[86:89], v42, s[44:45]
	global_load_dwordx4 v[90:93], v43, s[44:45]
	global_load_dwordx4 v[98:101], v44, s[44:45]
	global_load_dwordx4 v[102:105], v45, s[44:45]
	global_load_dwordx4 v[106:109], v46, s[44:45]
	global_load_dwordx4 v[140:143], v47, s[44:45]
	global_load_dwordx2 v[184:185], v48, s[46:47]
	global_load_dwordx2 v[186:187], v49, s[46:47]
	global_load_dwordx2 v[188:189], v50, s[46:47]
	global_load_dwordx2 v[190:191], v51, s[46:47]
	global_load_dwordx2 v[192:193], v52, s[46:47]
	global_load_dwordx2 v[194:195], v53, s[46:47]
	global_load_dwordx2 v[196:197], v54, s[46:47]
	global_load_dwordx2 v[198:199], v55, s[46:47]
	s_add_u32 s44, s44, 0xa000
	s_addc_u32 s45, s45, 0
	s_add_u32 s46, s46, 0x5000
	s_addc_u32 s47, s47, 0
	global_load_dwordx4 v[144:147], v40, s[44:45]
	global_load_dwordx4 v[148:151], v41, s[44:45]
	global_load_dwordx4 v[152:155], v42, s[44:45]
	global_load_dwordx4 v[156:159], v43, s[44:45]
	global_load_dwordx4 v[160:163], v44, s[44:45]
	global_load_dwordx4 v[164:167], v45, s[44:45]
	global_load_dwordx4 v[168:171], v46, s[44:45]
	global_load_dwordx4 v[180:183], v47, s[44:45]
	global_load_dwordx2 v[200:201], v48, s[46:47]
	global_load_dwordx2 v[202:203], v49, s[46:47]
	global_load_dwordx2 v[204:205], v50, s[46:47]
	global_load_dwordx2 v[206:207], v51, s[46:47]
	global_load_dwordx2 v[208:209], v52, s[46:47]
	global_load_dwordx2 v[210:211], v53, s[46:47]
	global_load_dwordx2 v[212:213], v54, s[46:47]
	global_load_dwordx2 v[214:215], v55, s[46:47]
	s_add_u32 s44, s44, 0xa000
	s_addc_u32 s45, s45, 0
	s_add_u32 s46, s46, 0x5000
	s_addc_u32 s47, s47, 0
	s_waitcnt vmcnt(16)
	v_lshlrev_b32_e32 v3, 16, v78
	v_and_b32_e32 v7, s71, v78
	v_lshlrev_b32_e32 v4, 16, v79
	v_and_b32_e32 v8, s71, v79
	v_lshlrev_b32_e32 v5, 16, v80
	v_and_b32_e32 v9, s71, v80
	v_lshlrev_b32_e32 v6, 16, v81
	v_and_b32_e32 v10, s71, v81
	v_sub_f32_e32 v3, 1.0, v3
	v_sub_f32_e32 v4, 1.0, v4
	v_sub_f32_e32 v5, 1.0, v5
	v_sub_f32_e32 v6, 1.0, v6
	v_fma_f32 v22, v3, v22, v7
	v_fma_f32 v23, v4, v23, v8
	v_fma_f32 v24, v5, v24, v9
	v_fma_f32 v25, v6, v25, v10
	v_lshlrev_b32_e32 v3, 16, v184
	v_and_b32_e32 v4, s71, v184
	v_lshlrev_b32_e32 v5, 16, v185
	v_and_b32_e32 v6, s71, v185
	v_mul_f32_e32 v3, v3, v22
	v_mul_f32_e32 v4, v4, v23
	v_mul_f32_e32 v5, v5, v24
	v_mul_f32_e32 v6, v6, v25
	v_cvt_pk_bf16_f32 v184, v3, v4
	v_cvt_pk_bf16_f32 v185, v5, v6
	global_store_dwordx2 v48, v[184:185], s[48:49]
	v_lshlrev_b32_e32 v3, 16, v82
	v_and_b32_e32 v7, s71, v82
	v_lshlrev_b32_e32 v4, 16, v83
	v_and_b32_e32 v8, s71, v83
	v_lshlrev_b32_e32 v5, 16, v84
	v_and_b32_e32 v9, s71, v84
	v_lshlrev_b32_e32 v6, 16, v85
	v_and_b32_e32 v10, s71, v85
	v_sub_f32_e32 v3, 1.0, v3
	v_sub_f32_e32 v4, 1.0, v4
	v_sub_f32_e32 v5, 1.0, v5
	v_sub_f32_e32 v6, 1.0, v6
	v_fma_f32 v22, v3, v22, v7
	v_fma_f32 v23, v4, v23, v8
	v_fma_f32 v24, v5, v24, v9
	v_fma_f32 v25, v6, v25, v10
	v_lshlrev_b32_e32 v3, 16, v186
	v_and_b32_e32 v4, s71, v186
	v_lshlrev_b32_e32 v5, 16, v187
	v_and_b32_e32 v6, s71, v187
	v_mul_f32_e32 v3, v3, v22
	v_mul_f32_e32 v4, v4, v23
	v_mul_f32_e32 v5, v5, v24
	v_mul_f32_e32 v6, v6, v25
	v_cvt_pk_bf16_f32 v186, v3, v4
	v_cvt_pk_bf16_f32 v187, v5, v6
	global_store_dwordx2 v49, v[186:187], s[48:49]
	v_lshlrev_b32_e32 v3, 16, v86
	v_and_b32_e32 v7, s71, v86
	v_lshlrev_b32_e32 v4, 16, v87
	v_and_b32_e32 v8, s71, v87
	v_lshlrev_b32_e32 v5, 16, v88
	v_and_b32_e32 v9, s71, v88
	v_lshlrev_b32_e32 v6, 16, v89
	v_and_b32_e32 v10, s71, v89
	v_sub_f32_e32 v3, 1.0, v3
	v_sub_f32_e32 v4, 1.0, v4
	v_sub_f32_e32 v5, 1.0, v5
	v_sub_f32_e32 v6, 1.0, v6
	v_fma_f32 v22, v3, v22, v7
	v_fma_f32 v23, v4, v23, v8
	v_fma_f32 v24, v5, v24, v9
	v_fma_f32 v25, v6, v25, v10
	v_lshlrev_b32_e32 v3, 16, v188
	v_and_b32_e32 v4, s71, v188
	v_lshlrev_b32_e32 v5, 16, v189
	v_and_b32_e32 v6, s71, v189
	v_mul_f32_e32 v3, v3, v22
	v_mul_f32_e32 v4, v4, v23
	v_mul_f32_e32 v5, v5, v24
	v_mul_f32_e32 v6, v6, v25
	v_cvt_pk_bf16_f32 v188, v3, v4
	v_cvt_pk_bf16_f32 v189, v5, v6
	global_store_dwordx2 v50, v[188:189], s[48:49]
	v_lshlrev_b32_e32 v3, 16, v90
	v_and_b32_e32 v7, s71, v90
	v_lshlrev_b32_e32 v4, 16, v91
	v_and_b32_e32 v8, s71, v91
	v_lshlrev_b32_e32 v5, 16, v92
	v_and_b32_e32 v9, s71, v92
	v_lshlrev_b32_e32 v6, 16, v93
	v_and_b32_e32 v10, s71, v93
	v_sub_f32_e32 v3, 1.0, v3
	v_sub_f32_e32 v4, 1.0, v4
	v_sub_f32_e32 v5, 1.0, v5
	v_sub_f32_e32 v6, 1.0, v6
	v_fma_f32 v22, v3, v22, v7
	v_fma_f32 v23, v4, v23, v8
	v_fma_f32 v24, v5, v24, v9
	v_fma_f32 v25, v6, v25, v10
	v_lshlrev_b32_e32 v3, 16, v190
	v_and_b32_e32 v4, s71, v190
	v_lshlrev_b32_e32 v5, 16, v191
	v_and_b32_e32 v6, s71, v191
	v_mul_f32_e32 v3, v3, v22
	v_mul_f32_e32 v4, v4, v23
	v_mul_f32_e32 v5, v5, v24
	v_mul_f32_e32 v6, v6, v25
	v_cvt_pk_bf16_f32 v190, v3, v4
	v_cvt_pk_bf16_f32 v191, v5, v6
	global_store_dwordx2 v51, v[190:191], s[48:49]
	v_lshlrev_b32_e32 v3, 16, v98
	v_and_b32_e32 v7, s71, v98
	v_lshlrev_b32_e32 v4, 16, v99
	v_and_b32_e32 v8, s71, v99
	v_lshlrev_b32_e32 v5, 16, v100
	v_and_b32_e32 v9, s71, v100
	v_lshlrev_b32_e32 v6, 16, v101
	v_and_b32_e32 v10, s71, v101
	v_sub_f32_e32 v3, 1.0, v3
	v_sub_f32_e32 v4, 1.0, v4
	v_sub_f32_e32 v5, 1.0, v5
	v_sub_f32_e32 v6, 1.0, v6
	v_fma_f32 v22, v3, v22, v7
	v_fma_f32 v23, v4, v23, v8
	v_fma_f32 v24, v5, v24, v9
	v_fma_f32 v25, v6, v25, v10
	v_lshlrev_b32_e32 v3, 16, v192
	v_and_b32_e32 v4, s71, v192
	v_lshlrev_b32_e32 v5, 16, v193
	v_and_b32_e32 v6, s71, v193
	v_mul_f32_e32 v3, v3, v22
	v_mul_f32_e32 v4, v4, v23
; DI unsigned cvt_pk_bf16(float lo, float hi) { unsigned r; asm volatile("v_cvt_pk_bf16_f32 %0, %1, %2" : "=v"(r) : "v"(lo), "v"(hi)); return r; }
; DI float bf2f(unsigned short b) { return __uint_as_float(((unsigned)b) << 16); }
; DI float bflo(unsigned w) { return __uint_as_float(w << 16); }
; DI float bfhi(unsigned w) { return __uint_as_float(w & 0xffff0000u); }
; DI void phase_lru_apply(const Frame& F, int j) {
;     ...
;         unsigned wv[2][16]; bf16_t gv[2][16];
; #pragma unroll
;         for (int i = 0; i < 16; ++i) { wv[0][i] = ab[(size_t)i * DRNN]; gv[0][i] = gp[(size_t)i * DRNN]; }
; #pragma unroll
;         for (int blk = 0; blk < 4; ++blk) { const int t0 = 16 * blk, cur = blk & 1;
;             if (t0 < len) {
;                 if (t0 + 16 < len) {
; #pragma unroll
;                     for (int i = 0; i < 16; ++i) { wv[cur ^ 1][i] = ab[(size_t)(t0 + 16 + i) * DRNN]; gv[cur ^ 1][i] = gp[(size_t)(t0 + 16 + i) * DRNN]; } }
; #pragma unroll
;                 for (int i = 0; i < 16; ++i) { h = (1.f - bflo(wv[cur][i])) * h + bfhi(wv[cur][i]); hp[(size_t)(t0 + i) * DRNN] = (bf16_t)(cvt_pk_bf16(bf2f(gv[cur][i]) * h, 0.f) & 0xffffu); } } }
	v_mul_f32_e32 v5, v5, v24
	v_mul_f32_e32 v6, v6, v25
	v_cvt_pk_bf16_f32 v192, v3, v4
	v_cvt_pk_bf16_f32 v193, v5, v6
	global_store_dwordx2 v52, v[192:193], s[48:49]
	v_lshlrev_b32_e32 v3, 16, v102
	v_and_b32_e32 v7, s71, v102
	v_lshlrev_b32_e32 v4, 16, v103
	v_and_b32_e32 v8, s71, v103
	v_lshlrev_b32_e32 v5, 16, v104
	v_and_b32_e32 v9, s71, v104
	v_lshlrev_b32_e32 v6, 16, v105
	v_and_b32_e32 v10, s71, v105
	v_sub_f32_e32 v3, 1.0, v3
	v_sub_f32_e32 v4, 1.0, v4
	v_sub_f32_e32 v5, 1.0, v5
	v_sub_f32_e32 v6, 1.0, v6
	v_fma_f32 v22, v3, v22, v7
	v_fma_f32 v23, v4, v23, v8
	v_fma_f32 v24, v5, v24, v9
	v_fma_f32 v25, v6, v25, v10
	v_lshlrev_b32_e32 v3, 16, v194
	v_and_b32_e32 v4, s71, v194
	v_lshlrev_b32_e32 v5, 16, v195
	v_and_b32_e32 v6, s71, v195
	v_mul_f32_e32 v3, v3, v22
	v_mul_f32_e32 v4, v4, v23
	v_mul_f32_e32 v5, v5, v24
	v_mul_f32_e32 v6, v6, v25
	v_cvt_pk_bf16_f32 v194, v3, v4
	v_cvt_pk_bf16_f32 v195, v5, v6
	global_store_dwordx2 v53, v[194:195], s[48:49]
	v_lshlrev_b32_e32 v3, 16, v106
	v_and_b32_e32 v7, s71, v106
	v_lshlrev_b32_e32 v4, 16, v107
	v_and_b32_e32 v8, s71, v107
	v_lshlrev_b32_e32 v5, 16, v108
	v_and_b32_e32 v9, s71, v108
	v_lshlrev_b32_e32 v6, 16, v109
	v_and_b32_e32 v10, s71, v109
	v_sub_f32_e32 v3, 1.0, v3
	v_sub_f32_e32 v4, 1.0, v4
	v_sub_f32_e32 v5, 1.0, v5
	v_sub_f32_e32 v6, 1.0, v6
	v_fma_f32 v22, v3, v22, v7
	v_fma_f32 v23, v4, v23, v8
	v_fma_f32 v24, v5, v24, v9
	v_fma_f32 v25, v6, v25, v10
	v_lshlrev_b32_e32 v3, 16, v196
	v_and_b32_e32 v4, s71, v196
	v_lshlrev_b32_e32 v5, 16, v197
	v_and_b32_e32 v6, s71, v197
	v_mul_f32_e32 v3, v3, v22
	v_mul_f32_e32 v4, v4, v23
	v_mul_f32_e32 v5, v5, v24
	v_mul_f32_e32 v6, v6, v25
	v_cvt_pk_bf16_f32 v196, v3, v4
	v_cvt_pk_bf16_f32 v197, v5, v6
	global_store_dwordx2 v54, v[196:197], s[48:49]
	v_lshlrev_b32_e32 v3, 16, v140
	v_and_b32_e32 v7, s71, v140
	v_lshlrev_b32_e32 v4, 16, v141
	v_and_b32_e32 v8, s71, v141
	v_lshlrev_b32_e32 v5, 16, v142
	v_and_b32_e32 v9, s71, v142
	v_lshlrev_b32_e32 v6, 16, v143
	v_and_b32_e32 v10, s71, v143
	v_sub_f32_e32 v3, 1.0, v3
	v_sub_f32_e32 v4, 1.0, v4
	v_sub_f32_e32 v5, 1.0, v5
	v_sub_f32_e32 v6, 1.0, v6
	v_fma_f32 v22, v3, v22, v7
	v_fma_f32 v23, v4, v23, v8
	v_fma_f32 v24, v5, v24, v9
	v_fma_f32 v25, v6, v25, v10
	v_lshlrev_b32_e32 v3, 16, v198
	v_and_b32_e32 v4, s71, v198
	v_lshlrev_b32_e32 v5, 16, v199
	v_and_b32_e32 v6, s71, v199
	v_mul_f32_e32 v3, v3, v22
	v_mul_f32_e32 v4, v4, v23
	v_mul_f32_e32 v5, v5, v24
	v_mul_f32_e32 v6, v6, v25
	v_cvt_pk_bf16_f32 v198, v3, v4
	v_cvt_pk_bf16_f32 v199, v5, v6
	global_store_dwordx2 v55, v[198:199], s[48:49]
	s_add_u32 s48, s48, 0x5000
	s_addc_u32 s49, s49, 0
.Llapp_main_loop:
	s_cmp_le_u32 s41, 1
	s_cbranch_scc1 .Llapp_main_last
	global_load_dwordx4 v[78:81], v40, s[44:45]
	global_load_dwordx4 v[82:85], v41, s[44:45]
	global_load_dwordx4 v[86:89], v42, s[44:45]
	global_load_dwordx4 v[90:93], v43, s[44:45]
	global_load_dwordx4 v[98:101], v44, s[44:45]
	global_load_dwordx4 v[102:105], v45, s[44:45]
	global_load_dwordx4 v[106:109], v46, s[44:45]
	global_load_dwordx4 v[140:143], v47, s[44:45]
	global_load_dwordx2 v[184:185], v48, s[46:47]
	global_load_dwordx2 v[186:187], v49, s[46:47]
	global_load_dwordx2 v[188:189], v50, s[46:47]
	global_load_dwordx2 v[190:191], v51, s[46:47]
	global_load_dwordx2 v[192:193], v52, s[46:47]
	global_load_dwordx2 v[194:195], v53, s[46:47]
	global_load_dwordx2 v[196:197], v54, s[46:47]
	global_load_dwordx2 v[198:199], v55, s[46:47]
	s_add_u32 s44, s44, 0xa000
	s_addc_u32 s45, s45, 0
	s_add_u32 s46, s46, 0x5000
	s_addc_u32 s47, s47, 0
	s_waitcnt vmcnt(24)
	v_lshlrev_b32_e32 v3, 16, v144
	v_and_b32_e32 v7, s71, v144
	v_lshlrev_b32_e32 v4, 16, v145
	v_and_b32_e32 v8, s71, v145
	v_lshlrev_b32_e32 v5, 16, v146
	v_and_b32_e32 v9, s71, v146
	v_lshlrev_b32_e32 v6, 16, v147
	v_and_b32_e32 v10, s71, v147
	v_sub_f32_e32 v3, 1.0, v3
	v_sub_f32_e32 v4, 1.0, v4
	v_sub_f32_e32 v5, 1.0, v5
	v_sub_f32_e32 v6, 1.0, v6
	v_fma_f32 v22, v3, v22, v7
	v_fma_f32 v23, v4, v23, v8
	v_fma_f32 v24, v5, v24, v9
	v_fma_f32 v25, v6, v25, v10
	v_lshlrev_b32_e32 v3, 16, v200
	v_and_b32_e32 v4, s71, v200
	v_lshlrev_b32_e32 v5, 16, v201
	v_and_b32_e32 v6, s71, v201
	v_mul_f32_e32 v3, v3, v22
	v_mul_f32_e32 v4, v4, v23
	v_mul_f32_e32 v5, v5, v24
	v_mul_f32_e32 v6, v6, v25
	v_cvt_pk_bf16_f32 v200, v3, v4
	v_cvt_pk_bf16_f32 v201, v5, v6
	global_store_dwordx2 v48, v[200:201], s[48:49]
	v_lshlrev_b32_e32 v3, 16, v148
	v_and_b32_e32 v7, s71, v148
	v_lshlrev_b32_e32 v4, 16, v149
	v_and_b32_e32 v8, s71, v149
	v_lshlrev_b32_e32 v5, 16, v150
	v_and_b32_e32 v9, s71, v150
	v_lshlrev_b32_e32 v6, 16, v151
	v_and_b32_e32 v10, s71, v151
	v_sub_f32_e32 v3, 1.0, v3
	v_sub_f32_e32 v4, 1.0, v4
	v_sub_f32_e32 v5, 1.0, v5
	v_sub_f32_e32 v6, 1.0, v6
	v_fma_f32 v22, v3, v22, v7
	v_fma_f32 v23, v4, v23, v8
	v_fma_f32 v24, v5, v24, v9
	v_fma_f32 v25, v6, v25, v10
	v_lshlrev_b32_e32 v3, 16, v202
	v_and_b32_e32 v4, s71, v202
	v_lshlrev_b32_e32 v5, 16, v203
	v_and_b32_e32 v6, s71, v203
	v_mul_f32_e32 v3, v3, v22
	v_mul_f32_e32 v4, v4, v23
	v_mul_f32_e32 v5, v5, v24
	v_mul_f32_e32 v6, v6, v25
	v_cvt_pk_bf16_f32 v202, v3, v4
	v_cvt_pk_bf16_f32 v203, v5, v6
	global_store_dwordx2 v49, v[202:203], s[48:49]
	v_lshlrev_b32_e32 v3, 16, v152
	v_and_b32_e32 v7, s71, v152
	v_lshlrev_b32_e32 v4, 16, v153
	v_and_b32_e32 v8, s71, v153
	v_lshlrev_b32_e32 v5, 16, v154
	v_and_b32_e32 v9, s71, v154
	v_lshlrev_b32_e32 v6, 16, v155
	v_and_b32_e32 v10, s71, v155
	v_sub_f32_e32 v3, 1.0, v3
	v_sub_f32_e32 v4, 1.0, v4
	v_sub_f32_e32 v5, 1.0, v5
	v_sub_f32_e32 v6, 1.0, v6
	v_fma_f32 v22, v3, v22, v7
	v_fma_f32 v23, v4, v23, v8
	v_fma_f32 v24, v5, v24, v9
; DI unsigned cvt_pk_bf16(float lo, float hi) { unsigned r; asm volatile("v_cvt_pk_bf16_f32 %0, %1, %2" : "=v"(r) : "v"(lo), "v"(hi)); return r; }
; DI float bf2f(unsigned short b) { return __uint_as_float(((unsigned)b) << 16); }
; DI float bflo(unsigned w) { return __uint_as_float(w << 16); }
; DI float bfhi(unsigned w) { return __uint_as_float(w & 0xffff0000u); }
; DI void phase_lru_apply(const Frame& F, int j) {
;     ...
;         unsigned wv[2][16]; bf16_t gv[2][16];
; #pragma unroll
;         for (int i = 0; i < 16; ++i) { wv[0][i] = ab[(size_t)i * DRNN]; gv[0][i] = gp[(size_t)i * DRNN]; }
; #pragma unroll
;         for (int blk = 0; blk < 4; ++blk) { const int t0 = 16 * blk, cur = blk & 1;
;             if (t0 < len) {
;                 if (t0 + 16 < len) {
; #pragma unroll
;                     for (int i = 0; i < 16; ++i) { wv[cur ^ 1][i] = ab[(size_t)(t0 + 16 + i) * DRNN]; gv[cur ^ 1][i] = gp[(size_t)(t0 + 16 + i) * DRNN]; } }
; #pragma unroll
;                 for (int i = 0; i < 16; ++i) { h = (1.f - bflo(wv[cur][i])) * h + bfhi(wv[cur][i]); hp[(size_t)(t0 + i) * DRNN] = (bf16_t)(cvt_pk_bf16(bf2f(gv[cur][i]) * h, 0.f) & 0xffffu); } } }
	v_fma_f32 v25, v6, v25, v10
	v_lshlrev_b32_e32 v3, 16, v204
	v_and_b32_e32 v4, s71, v204
	v_lshlrev_b32_e32 v5, 16, v205
	v_and_b32_e32 v6, s71, v205
	v_mul_f32_e32 v3, v3, v22
	v_mul_f32_e32 v4, v4, v23
	v_mul_f32_e32 v5, v5, v24
	v_mul_f32_e32 v6, v6, v25
	v_cvt_pk_bf16_f32 v204, v3, v4
	v_cvt_pk_bf16_f32 v205, v5, v6
	global_store_dwordx2 v50, v[204:205], s[48:49]
	v_lshlrev_b32_e32 v3, 16, v156
	v_and_b32_e32 v7, s71, v156
	v_lshlrev_b32_e32 v4, 16, v157
	v_and_b32_e32 v8, s71, v157
	v_lshlrev_b32_e32 v5, 16, v158
	v_and_b32_e32 v9, s71, v158
	v_lshlrev_b32_e32 v6, 16, v159
	v_and_b32_e32 v10, s71, v159
	v_sub_f32_e32 v3, 1.0, v3
	v_sub_f32_e32 v4, 1.0, v4
	v_sub_f32_e32 v5, 1.0, v5
	v_sub_f32_e32 v6, 1.0, v6
	v_fma_f32 v22, v3, v22, v7
	v_fma_f32 v23, v4, v23, v8
	v_fma_f32 v24, v5, v24, v9
	v_fma_f32 v25, v6, v25, v10
	v_lshlrev_b32_e32 v3, 16, v206
	v_and_b32_e32 v4, s71, v206
	v_lshlrev_b32_e32 v5, 16, v207
	v_and_b32_e32 v6, s71, v207
	v_mul_f32_e32 v3, v3, v22
	v_mul_f32_e32 v4, v4, v23
	v_mul_f32_e32 v5, v5, v24
	v_mul_f32_e32 v6, v6, v25
	v_cvt_pk_bf16_f32 v206, v3, v4
	v_cvt_pk_bf16_f32 v207, v5, v6
	global_store_dwordx2 v51, v[206:207], s[48:49]
	v_lshlrev_b32_e32 v3, 16, v160
	v_and_b32_e32 v7, s71, v160
	v_lshlrev_b32_e32 v4, 16, v161
	v_and_b32_e32 v8, s71, v161
	v_lshlrev_b32_e32 v5, 16, v162
	v_and_b32_e32 v9, s71, v162
	v_lshlrev_b32_e32 v6, 16, v163
	v_and_b32_e32 v10, s71, v163
	v_sub_f32_e32 v3, 1.0, v3
	v_sub_f32_e32 v4, 1.0, v4
	v_sub_f32_e32 v5, 1.0, v5
	v_sub_f32_e32 v6, 1.0, v6
	v_fma_f32 v22, v3, v22, v7
	v_fma_f32 v23, v4, v23, v8
	v_fma_f32 v24, v5, v24, v9
	v_fma_f32 v25, v6, v25, v10
	v_lshlrev_b32_e32 v3, 16, v208
	v_and_b32_e32 v4, s71, v208
	v_lshlrev_b32_e32 v5, 16, v209
	v_and_b32_e32 v6, s71, v209
	v_mul_f32_e32 v3, v3, v22
	v_mul_f32_e32 v4, v4, v23
	v_mul_f32_e32 v5, v5, v24
	v_mul_f32_e32 v6, v6, v25
	v_cvt_pk_bf16_f32 v208, v3, v4
	v_cvt_pk_bf16_f32 v209, v5, v6
	global_store_dwordx2 v52, v[208:209], s[48:49]
	v_lshlrev_b32_e32 v3, 16, v164
	v_and_b32_e32 v7, s71, v164
	v_lshlrev_b32_e32 v4, 16, v165
	v_and_b32_e32 v8, s71, v165
	v_lshlrev_b32_e32 v5, 16, v166
	v_and_b32_e32 v9, s71, v166
	v_lshlrev_b32_e32 v6, 16, v167
	v_and_b32_e32 v10, s71, v167
	v_sub_f32_e32 v3, 1.0, v3
	v_sub_f32_e32 v4, 1.0, v4
	v_sub_f32_e32 v5, 1.0, v5
	v_sub_f32_e32 v6, 1.0, v6
	v_fma_f32 v22, v3, v22, v7
	v_fma_f32 v23, v4, v23, v8
	v_fma_f32 v24, v5, v24, v9
	v_fma_f32 v25, v6, v25, v10
	v_lshlrev_b32_e32 v3, 16, v210
	v_and_b32_e32 v4, s71, v210
	v_lshlrev_b32_e32 v5, 16, v211
	v_and_b32_e32 v6, s71, v211
	v_mul_f32_e32 v3, v3, v22
	v_mul_f32_e32 v4, v4, v23
	v_mul_f32_e32 v5, v5, v24
	v_mul_f32_e32 v6, v6, v25
	v_cvt_pk_bf16_f32 v210, v3, v4
	v_cvt_pk_bf16_f32 v211, v5, v6
	global_store_dwordx2 v53, v[210:211], s[48:49]
	v_lshlrev_b32_e32 v3, 16, v168
	v_and_b32_e32 v7, s71, v168
	v_lshlrev_b32_e32 v4, 16, v169
	v_and_b32_e32 v8, s71, v169
	v_lshlrev_b32_e32 v5, 16, v170
	v_and_b32_e32 v9, s71, v170
	v_lshlrev_b32_e32 v6, 16, v171
	v_and_b32_e32 v10, s71, v171
	v_sub_f32_e32 v3, 1.0, v3
	v_sub_f32_e32 v4, 1.0, v4
	v_sub_f32_e32 v5, 1.0, v5
	v_sub_f32_e32 v6, 1.0, v6
	v_fma_f32 v22, v3, v22, v7
	v_fma_f32 v23, v4, v23, v8
	v_fma_f32 v24, v5, v24, v9
	v_fma_f32 v25, v6, v25, v10
	v_lshlrev_b32_e32 v3, 16, v212
	v_and_b32_e32 v4, s71, v212
	v_lshlrev_b32_e32 v5, 16, v213
	v_and_b32_e32 v6, s71, v213
	v_mul_f32_e32 v3, v3, v22
	v_mul_f32_e32 v4, v4, v23
	v_mul_f32_e32 v5, v5, v24
	v_mul_f32_e32 v6, v6, v25
	v_cvt_pk_bf16_f32 v212, v3, v4
	v_cvt_pk_bf16_f32 v213, v5, v6
	global_store_dwordx2 v54, v[212:213], s[48:49]
	v_lshlrev_b32_e32 v3, 16, v180
	v_and_b32_e32 v7, s71, v180
	v_lshlrev_b32_e32 v4, 16, v181
	v_and_b32_e32 v8, s71, v181
	v_lshlrev_b32_e32 v5, 16, v182
	v_and_b32_e32 v9, s71, v182
	v_lshlrev_b32_e32 v6, 16, v183
	v_and_b32_e32 v10, s71, v183
	v_sub_f32_e32 v3, 1.0, v3
	v_sub_f32_e32 v4, 1.0, v4
	v_sub_f32_e32 v5, 1.0, v5
	v_sub_f32_e32 v6, 1.0, v6
	v_fma_f32 v22, v3, v22, v7
	v_fma_f32 v23, v4, v23, v8
	v_fma_f32 v24, v5, v24, v9
	v_fma_f32 v25, v6, v25, v10
	v_lshlrev_b32_e32 v3, 16, v214
	v_and_b32_e32 v4, s71, v214
	v_lshlrev_b32_e32 v5, 16, v215
	v_and_b32_e32 v6, s71, v215
	v_mul_f32_e32 v3, v3, v22
	v_mul_f32_e32 v4, v4, v23
	v_mul_f32_e32 v5, v5, v24
	v_mul_f32_e32 v6, v6, v25
	v_cvt_pk_bf16_f32 v214, v3, v4
	v_cvt_pk_bf16_f32 v215, v5, v6
	global_store_dwordx2 v55, v[214:215], s[48:49]
	s_add_u32 s48, s48, 0x5000
	s_addc_u32 s49, s49, 0
	global_load_dwordx4 v[144:147], v40, s[44:45]
	global_load_dwordx4 v[148:151], v41, s[44:45]
	global_load_dwordx4 v[152:155], v42, s[44:45]
	global_load_dwordx4 v[156:159], v43, s[44:45]
	global_load_dwordx4 v[160:163], v44, s[44:45]
	global_load_dwordx4 v[164:167], v45, s[44:45]
	global_load_dwordx4 v[168:171], v46, s[44:45]
	global_load_dwordx4 v[180:183], v47, s[44:45]
	global_load_dwordx2 v[200:201], v48, s[46:47]
	global_load_dwordx2 v[202:203], v49, s[46:47]
	global_load_dwordx2 v[204:205], v50, s[46:47]
	global_load_dwordx2 v[206:207], v51, s[46:47]
	global_load_dwordx2 v[208:209], v52, s[46:47]
	global_load_dwordx2 v[210:211], v53, s[46:47]
	global_load_dwordx2 v[212:213], v54, s[46:47]
	global_load_dwordx2 v[214:215], v55, s[46:47]
	s_add_u32 s44, s44, 0xa000
	s_addc_u32 s45, s45, 0
	s_add_u32 s46, s46, 0x5000
	s_addc_u32 s47, s47, 0
	s_waitcnt vmcnt(24)
; DI unsigned cvt_pk_bf16(float lo, float hi) { unsigned r; asm volatile("v_cvt_pk_bf16_f32 %0, %1, %2" : "=v"(r) : "v"(lo), "v"(hi)); return r; }
; DI float bf2f(unsigned short b) { return __uint_as_float(((unsigned)b) << 16); }
; DI float bflo(unsigned w) { return __uint_as_float(w << 16); }
; DI float bfhi(unsigned w) { return __uint_as_float(w & 0xffff0000u); }
; DI void phase_lru_apply(const Frame& F, int j) {
;     ...
;         unsigned wv[2][16]; bf16_t gv[2][16];
; #pragma unroll
;         for (int i = 0; i < 16; ++i) { wv[0][i] = ab[(size_t)i * DRNN]; gv[0][i] = gp[(size_t)i * DRNN]; }
; #pragma unroll
;         for (int blk = 0; blk < 4; ++blk) { const int t0 = 16 * blk, cur = blk & 1;
;             if (t0 < len) {
;                 if (t0 + 16 < len) {
; #pragma unroll
;                     for (int i = 0; i < 16; ++i) { wv[cur ^ 1][i] = ab[(size_t)(t0 + 16 + i) * DRNN]; gv[cur ^ 1][i] = gp[(size_t)(t0 + 16 + i) * DRNN]; } }
; #pragma unroll
;                 for (int i = 0; i < 16; ++i) { h = (1.f - bflo(wv[cur][i])) * h + bfhi(wv[cur][i]); hp[(size_t)(t0 + i) * DRNN] = (bf16_t)(cvt_pk_bf16(bf2f(gv[cur][i]) * h, 0.f) & 0xffffu); } } }
	v_lshlrev_b32_e32 v3, 16, v78
	v_and_b32_e32 v7, s71, v78
	v_lshlrev_b32_e32 v4, 16, v79
	v_and_b32_e32 v8, s71, v79
	v_lshlrev_b32_e32 v5, 16, v80
	v_and_b32_e32 v9, s71, v80
	v_lshlrev_b32_e32 v6, 16, v81
	v_and_b32_e32 v10, s71, v81
	v_sub_f32_e32 v3, 1.0, v3
	v_sub_f32_e32 v4, 1.0, v4
	v_sub_f32_e32 v5, 1.0, v5
	v_sub_f32_e32 v6, 1.0, v6
	v_fma_f32 v22, v3, v22, v7
	v_fma_f32 v23, v4, v23, v8
	v_fma_f32 v24, v5, v24, v9
	v_fma_f32 v25, v6, v25, v10
	v_lshlrev_b32_e32 v3, 16, v184
	v_and_b32_e32 v4, s71, v184
	v_lshlrev_b32_e32 v5, 16, v185
	v_and_b32_e32 v6, s71, v185
	v_mul_f32_e32 v3, v3, v22
	v_mul_f32_e32 v4, v4, v23
	v_mul_f32_e32 v5, v5, v24
	v_mul_f32_e32 v6, v6, v25
	v_cvt_pk_bf16_f32 v184, v3, v4
	v_cvt_pk_bf16_f32 v185, v5, v6
	global_store_dwordx2 v48, v[184:185], s[48:49]
	v_lshlrev_b32_e32 v3, 16, v82
	v_and_b32_e32 v7, s71, v82
	v_lshlrev_b32_e32 v4, 16, v83
	v_and_b32_e32 v8, s71, v83
	v_lshlrev_b32_e32 v5, 16, v84
	v_and_b32_e32 v9, s71, v84
	v_lshlrev_b32_e32 v6, 16, v85
	v_and_b32_e32 v10, s71, v85
	v_sub_f32_e32 v3, 1.0, v3
	v_sub_f32_e32 v4, 1.0, v4
	v_sub_f32_e32 v5, 1.0, v5
	v_sub_f32_e32 v6, 1.0, v6
	v_fma_f32 v22, v3, v22, v7
	v_fma_f32 v23, v4, v23, v8
	v_fma_f32 v24, v5, v24, v9
	v_fma_f32 v25, v6, v25, v10
	v_lshlrev_b32_e32 v3, 16, v186
	v_and_b32_e32 v4, s71, v186
	v_lshlrev_b32_e32 v5, 16, v187
	v_and_b32_e32 v6, s71, v187
	v_mul_f32_e32 v3, v3, v22
	v_mul_f32_e32 v4, v4, v23
	v_mul_f32_e32 v5, v5, v24
	v_mul_f32_e32 v6, v6, v25
	v_cvt_pk_bf16_f32 v186, v3, v4
	v_cvt_pk_bf16_f32 v187, v5, v6
	global_store_dwordx2 v49, v[186:187], s[48:49]
	v_lshlrev_b32_e32 v3, 16, v86
	v_and_b32_e32 v7, s71, v86
	v_lshlrev_b32_e32 v4, 16, v87
	v_and_b32_e32 v8, s71, v87
	v_lshlrev_b32_e32 v5, 16, v88
	v_and_b32_e32 v9, s71, v88
	v_lshlrev_b32_e32 v6, 16, v89
	v_and_b32_e32 v10, s71, v89
	v_sub_f32_e32 v3, 1.0, v3
	v_sub_f32_e32 v4, 1.0, v4
	v_sub_f32_e32 v5, 1.0, v5
	v_sub_f32_e32 v6, 1.0, v6
	v_fma_f32 v22, v3, v22, v7
	v_fma_f32 v23, v4, v23, v8
	v_fma_f32 v24, v5, v24, v9
	v_fma_f32 v25, v6, v25, v10
	v_lshlrev_b32_e32 v3, 16, v188
	v_and_b32_e32 v4, s71, v188
	v_lshlrev_b32_e32 v5, 16, v189
	v_and_b32_e32 v6, s71, v189
	v_mul_f32_e32 v3, v3, v22
	v_mul_f32_e32 v4, v4, v23
	v_mul_f32_e32 v5, v5, v24
	v_mul_f32_e32 v6, v6, v25
	v_cvt_pk_bf16_f32 v188, v3, v4
	v_cvt_pk_bf16_f32 v189, v5, v6
	global_store_dwordx2 v50, v[188:189], s[48:49]
	v_lshlrev_b32_e32 v3, 16, v90
	v_and_b32_e32 v7, s71, v90
	v_lshlrev_b32_e32 v4, 16, v91
	v_and_b32_e32 v8, s71, v91
	v_lshlrev_b32_e32 v5, 16, v92
	v_and_b32_e32 v9, s71, v92
	v_lshlrev_b32_e32 v6, 16, v93
	v_and_b32_e32 v10, s71, v93
	v_sub_f32_e32 v3, 1.0, v3
	v_sub_f32_e32 v4, 1.0, v4
	v_sub_f32_e32 v5, 1.0, v5
	v_sub_f32_e32 v6, 1.0, v6
	v_fma_f32 v22, v3, v22, v7
	v_fma_f32 v23, v4, v23, v8
	v_fma_f32 v24, v5, v24, v9
	v_fma_f32 v25, v6, v25, v10
	v_lshlrev_b32_e32 v3, 16, v190
	v_and_b32_e32 v4, s71, v190
	v_lshlrev_b32_e32 v5, 16, v191
	v_and_b32_e32 v6, s71, v191
	v_mul_f32_e32 v3, v3, v22
	v_mul_f32_e32 v4, v4, v23
	v_mul_f32_e32 v5, v5, v24
	v_mul_f32_e32 v6, v6, v25
	v_cvt_pk_bf16_f32 v190, v3, v4
	v_cvt_pk_bf16_f32 v191, v5, v6
	global_store_dwordx2 v51, v[190:191], s[48:49]
	v_lshlrev_b32_e32 v3, 16, v98
	v_and_b32_e32 v7, s71, v98
	v_lshlrev_b32_e32 v4, 16, v99
	v_and_b32_e32 v8, s71, v99
	v_lshlrev_b32_e32 v5, 16, v100
	v_and_b32_e32 v9, s71, v100
	v_lshlrev_b32_e32 v6, 16, v101
	v_and_b32_e32 v10, s71, v101
	v_sub_f32_e32 v3, 1.0, v3
	v_sub_f32_e32 v4, 1.0, v4
	v_sub_f32_e32 v5, 1.0, v5
	v_sub_f32_e32 v6, 1.0, v6
	v_fma_f32 v22, v3, v22, v7
	v_fma_f32 v23, v4, v23, v8
	v_fma_f32 v24, v5, v24, v9
	v_fma_f32 v25, v6, v25, v10
	v_lshlrev_b32_e32 v3, 16, v192
	v_and_b32_e32 v4, s71, v192
	v_lshlrev_b32_e32 v5, 16, v193
	v_and_b32_e32 v6, s71, v193
	v_mul_f32_e32 v3, v3, v22
	v_mul_f32_e32 v4, v4, v23
	v_mul_f32_e32 v5, v5, v24
	v_mul_f32_e32 v6, v6, v25
	v_cvt_pk_bf16_f32 v192, v3, v4
	v_cvt_pk_bf16_f32 v193, v5, v6
	global_store_dwordx2 v52, v[192:193], s[48:49]
	v_lshlrev_b32_e32 v3, 16, v102
	v_and_b32_e32 v7, s71, v102
	v_lshlrev_b32_e32 v4, 16, v103
	v_and_b32_e32 v8, s71, v103
	v_lshlrev_b32_e32 v5, 16, v104
	v_and_b32_e32 v9, s71, v104
	v_lshlrev_b32_e32 v6, 16, v105
	v_and_b32_e32 v10, s71, v105
	v_sub_f32_e32 v3, 1.0, v3
	v_sub_f32_e32 v4, 1.0, v4
	v_sub_f32_e32 v5, 1.0, v5
	v_sub_f32_e32 v6, 1.0, v6
	v_fma_f32 v22, v3, v22, v7
	v_fma_f32 v23, v4, v23, v8
	v_fma_f32 v24, v5, v24, v9
	v_fma_f32 v25, v6, v25, v10
	v_lshlrev_b32_e32 v3, 16, v194
	v_and_b32_e32 v4, s71, v194
	v_lshlrev_b32_e32 v5, 16, v195
	v_and_b32_e32 v6, s71, v195
	v_mul_f32_e32 v3, v3, v22
	v_mul_f32_e32 v4, v4, v23
	v_mul_f32_e32 v5, v5, v24
	v_mul_f32_e32 v6, v6, v25
	v_cvt_pk_bf16_f32 v194, v3, v4
	v_cvt_pk_bf16_f32 v195, v5, v6
	global_store_dwordx2 v53, v[194:195], s[48:49]
	v_lshlrev_b32_e32 v3, 16, v106
	v_and_b32_e32 v7, s71, v106
	v_lshlrev_b32_e32 v4, 16, v107
	v_and_b32_e32 v8, s71, v107
	v_lshlrev_b32_e32 v5, 16, v108
	v_and_b32_e32 v9, s71, v108
	v_lshlrev_b32_e32 v6, 16, v109
	v_and_b32_e32 v10, s71, v109
	v_sub_f32_e32 v3, 1.0, v3
	v_sub_f32_e32 v4, 1.0, v4
	v_sub_f32_e32 v5, 1.0, v5
	v_sub_f32_e32 v6, 1.0, v6
	v_fma_f32 v22, v3, v22, v7
	v_fma_f32 v23, v4, v23, v8
	v_fma_f32 v24, v5, v24, v9
	v_fma_f32 v25, v6, v25, v10
	v_lshlrev_b32_e32 v3, 16, v196
	v_and_b32_e32 v4, s71, v196
	v_lshlrev_b32_e32 v5, 16, v197
	v_and_b32_e32 v6, s71, v197
	v_mul_f32_e32 v3, v3, v22
	v_mul_f32_e32 v4, v4, v23
	v_mul_f32_e32 v5, v5, v24
	v_mul_f32_e32 v6, v6, v25
	v_cvt_pk_bf16_f32 v196, v3, v4
	v_cvt_pk_bf16_f32 v197, v5, v6
	global_store_dwordx2 v54, v[196:197], s[48:49]
	v_lshlrev_b32_e32 v3, 16, v140
	v_and_b32_e32 v7, s71, v140
	v_lshlrev_b32_e32 v4, 16, v141
	v_and_b32_e32 v8, s71, v141
	v_lshlrev_b32_e32 v5, 16, v142
	v_and_b32_e32 v9, s71, v142
	v_lshlrev_b32_e32 v6, 16, v143
	v_and_b32_e32 v10, s71, v143
	v_sub_f32_e32 v3, 1.0, v3
	v_sub_f32_e32 v4, 1.0, v4
	v_sub_f32_e32 v5, 1.0, v5
	v_sub_f32_e32 v6, 1.0, v6
	v_fma_f32 v22, v3, v22, v7
	v_fma_f32 v23, v4, v23, v8
	v_fma_f32 v24, v5, v24, v9
	v_fma_f32 v25, v6, v25, v10
	v_lshlrev_b32_e32 v3, 16, v198
	v_and_b32_e32 v4, s71, v198
	v_lshlrev_b32_e32 v5, 16, v199
	v_and_b32_e32 v6, s71, v199
	v_mul_f32_e32 v3, v3, v22
	v_mul_f32_e32 v4, v4, v23
	v_mul_f32_e32 v5, v5, v24
	v_mul_f32_e32 v6, v6, v25
	v_cvt_pk_bf16_f32 v198, v3, v4
	v_cvt_pk_bf16_f32 v199, v5, v6
	global_store_dwordx2 v55, v[198:199], s[48:49]
	s_add_u32 s48, s48, 0x5000
	s_addc_u32 s49, s49, 0
	s_sub_i32 s41, s41, 1
	s_branch .Llapp_main_loop
; DI unsigned cvt_pk_bf16(float lo, float hi) { unsigned r; asm volatile("v_cvt_pk_bf16_f32 %0, %1, %2" : "=v"(r) : "v"(lo), "v"(hi)); return r; }
; DI float bf2f(unsigned short b) { return __uint_as_float(((unsigned)b) << 16); }
; DI float bflo(unsigned w) { return __uint_as_float(w << 16); }
; DI float bfhi(unsigned w) { return __uint_as_float(w & 0xffff0000u); }
; DI void phase_lru_apply(const Frame& F, int j) {
;     ...
;         for (int blk = 0; blk < 4; ++blk) { const int t0 = 16 * blk, cur = blk & 1;
;             if (t0 < len) {
;                 if (t0 + 16 < len) {
; #pragma unroll
;                     for (int i = 0; i < 16; ++i) { wv[cur ^ 1][i] = ab[(size_t)(t0 + 16 + i) * DRNN]; gv[cur ^ 1][i] = gp[(size_t)(t0 + 16 + i) * DRNN]; } }
; #pragma unroll
;                 for (int i = 0; i < 16; ++i) { h = (1.f - bflo(wv[cur][i])) * h + bfhi(wv[cur][i]); hp[(size_t)(t0 + i) * DRNN] = (bf16_t)(cvt_pk_bf16(bf2f(gv[cur][i]) * h, 0.f) & 0xffffu); } } }
;         if (lastc) *ho = h; }
.Llapp_main_last:
	s_waitcnt vmcnt(8)
	v_lshlrev_b32_e32 v3, 16, v144
	v_and_b32_e32 v7, s71, v144
	v_lshlrev_b32_e32 v4, 16, v145
	v_and_b32_e32 v8, s71, v145
	v_lshlrev_b32_e32 v5, 16, v146
	v_and_b32_e32 v9, s71, v146
	v_lshlrev_b32_e32 v6, 16, v147
	v_and_b32_e32 v10, s71, v147
	v_sub_f32_e32 v3, 1.0, v3
	v_sub_f32_e32 v4, 1.0, v4
	v_sub_f32_e32 v5, 1.0, v5
	v_sub_f32_e32 v6, 1.0, v6
	v_fma_f32 v22, v3, v22, v7
	v_fma_f32 v23, v4, v23, v8
	v_fma_f32 v24, v5, v24, v9
	v_fma_f32 v25, v6, v25, v10
	v_lshlrev_b32_e32 v3, 16, v200
	v_and_b32_e32 v4, s71, v200
	v_lshlrev_b32_e32 v5, 16, v201
	v_and_b32_e32 v6, s71, v201
	v_mul_f32_e32 v3, v3, v22
	v_mul_f32_e32 v4, v4, v23
	v_mul_f32_e32 v5, v5, v24
	v_mul_f32_e32 v6, v6, v25
	v_cvt_pk_bf16_f32 v200, v3, v4
	v_cvt_pk_bf16_f32 v201, v5, v6
	global_store_dwordx2 v48, v[200:201], s[48:49]
	v_lshlrev_b32_e32 v3, 16, v148
	v_and_b32_e32 v7, s71, v148
	v_lshlrev_b32_e32 v4, 16, v149
	v_and_b32_e32 v8, s71, v149
	v_lshlrev_b32_e32 v5, 16, v150
	v_and_b32_e32 v9, s71, v150
	v_lshlrev_b32_e32 v6, 16, v151
	v_and_b32_e32 v10, s71, v151
	v_sub_f32_e32 v3, 1.0, v3
	v_sub_f32_e32 v4, 1.0, v4
	v_sub_f32_e32 v5, 1.0, v5
	v_sub_f32_e32 v6, 1.0, v6
	v_fma_f32 v22, v3, v22, v7
	v_fma_f32 v23, v4, v23, v8
	v_fma_f32 v24, v5, v24, v9
	v_fma_f32 v25, v6, v25, v10
	v_lshlrev_b32_e32 v3, 16, v202
	v_and_b32_e32 v4, s71, v202
	v_lshlrev_b32_e32 v5, 16, v203
	v_and_b32_e32 v6, s71, v203
	v_mul_f32_e32 v3, v3, v22
	v_mul_f32_e32 v4, v4, v23
	v_mul_f32_e32 v5, v5, v24
	v_mul_f32_e32 v6, v6, v25
	v_cvt_pk_bf16_f32 v202, v3, v4
	v_cvt_pk_bf16_f32 v203, v5, v6
	global_store_dwordx2 v49, v[202:203], s[48:49]
	v_lshlrev_b32_e32 v3, 16, v152
	v_and_b32_e32 v7, s71, v152
	v_lshlrev_b32_e32 v4, 16, v153
	v_and_b32_e32 v8, s71, v153
	v_lshlrev_b32_e32 v5, 16, v154
	v_and_b32_e32 v9, s71, v154
	v_lshlrev_b32_e32 v6, 16, v155
	v_and_b32_e32 v10, s71, v155
	v_sub_f32_e32 v3, 1.0, v3
	v_sub_f32_e32 v4, 1.0, v4
	v_sub_f32_e32 v5, 1.0, v5
	v_sub_f32_e32 v6, 1.0, v6
	v_fma_f32 v22, v3, v22, v7
	v_fma_f32 v23, v4, v23, v8
	v_fma_f32 v24, v5, v24, v9
	v_fma_f32 v25, v6, v25, v10
	v_lshlrev_b32_e32 v3, 16, v204
	v_and_b32_e32 v4, s71, v204
	v_lshlrev_b32_e32 v5, 16, v205
	v_and_b32_e32 v6, s71, v205
	v_mul_f32_e32 v3, v3, v22
	v_mul_f32_e32 v4, v4, v23
	v_mul_f32_e32 v5, v5, v24
	v_mul_f32_e32 v6, v6, v25
	v_cvt_pk_bf16_f32 v204, v3, v4
	v_cvt_pk_bf16_f32 v205, v5, v6
	global_store_dwordx2 v50, v[204:205], s[48:49]
	v_lshlrev_b32_e32 v3, 16, v156
	v_and_b32_e32 v7, s71, v156
	v_lshlrev_b32_e32 v4, 16, v157
	v_and_b32_e32 v8, s71, v157
	v_lshlrev_b32_e32 v5, 16, v158
	v_and_b32_e32 v9, s71, v158
	v_lshlrev_b32_e32 v6, 16, v159
	v_and_b32_e32 v10, s71, v159
	v_sub_f32_e32 v3, 1.0, v3
	v_sub_f32_e32 v4, 1.0, v4
	v_sub_f32_e32 v5, 1.0, v5
	v_sub_f32_e32 v6, 1.0, v6
	v_fma_f32 v22, v3, v22, v7
	v_fma_f32 v23, v4, v23, v8
	v_fma_f32 v24, v5, v24, v9
	v_fma_f32 v25, v6, v25, v10
	v_lshlrev_b32_e32 v3, 16, v206
	v_and_b32_e32 v4, s71, v206
	v_lshlrev_b32_e32 v5, 16, v207
	v_and_b32_e32 v6, s71, v207
	v_mul_f32_e32 v3, v3, v22
	v_mul_f32_e32 v4, v4, v23
	v_mul_f32_e32 v5, v5, v24
	v_mul_f32_e32 v6, v6, v25
	v_cvt_pk_bf16_f32 v206, v3, v4
	v_cvt_pk_bf16_f32 v207, v5, v6
	global_store_dwordx2 v51, v[206:207], s[48:49]
	v_lshlrev_b32_e32 v3, 16, v160
	v_and_b32_e32 v7, s71, v160
	v_lshlrev_b32_e32 v4, 16, v161
	v_and_b32_e32 v8, s71, v161
	v_lshlrev_b32_e32 v5, 16, v162
	v_and_b32_e32 v9, s71, v162
	v_lshlrev_b32_e32 v6, 16, v163
	v_and_b32_e32 v10, s71, v163
	v_sub_f32_e32 v3, 1.0, v3
	v_sub_f32_e32 v4, 1.0, v4
	v_sub_f32_e32 v5, 1.0, v5
	v_sub_f32_e32 v6, 1.0, v6
	v_fma_f32 v22, v3, v22, v7
	v_fma_f32 v23, v4, v23, v8
	v_fma_f32 v24, v5, v24, v9
	v_fma_f32 v25, v6, v25, v10
	v_lshlrev_b32_e32 v3, 16, v208
	v_and_b32_e32 v4, s71, v208
	v_lshlrev_b32_e32 v5, 16, v209
	v_and_b32_e32 v6, s71, v209
	v_mul_f32_e32 v3, v3, v22
	v_mul_f32_e32 v4, v4, v23
	v_mul_f32_e32 v5, v5, v24
	v_mul_f32_e32 v6, v6, v25
	v_cvt_pk_bf16_f32 v208, v3, v4
	v_cvt_pk_bf16_f32 v209, v5, v6
	global_store_dwordx2 v52, v[208:209], s[48:49]
	v_lshlrev_b32_e32 v3, 16, v164
	v_and_b32_e32 v7, s71, v164
	v_lshlrev_b32_e32 v4, 16, v165
	v_and_b32_e32 v8, s71, v165
	v_lshlrev_b32_e32 v5, 16, v166
	v_and_b32_e32 v9, s71, v166
	v_lshlrev_b32_e32 v6, 16, v167
	v_and_b32_e32 v10, s71, v167
	v_sub_f32_e32 v3, 1.0, v3
	v_sub_f32_e32 v4, 1.0, v4
	v_sub_f32_e32 v5, 1.0, v5
	v_sub_f32_e32 v6, 1.0, v6
	v_fma_f32 v22, v3, v22, v7
	v_fma_f32 v23, v4, v23, v8
	v_fma_f32 v24, v5, v24, v9
	v_fma_f32 v25, v6, v25, v10
	v_lshlrev_b32_e32 v3, 16, v210
	v_and_b32_e32 v4, s71, v210
	v_lshlrev_b32_e32 v5, 16, v211
	v_and_b32_e32 v6, s71, v211
	v_mul_f32_e32 v3, v3, v22
	v_mul_f32_e32 v4, v4, v23
	v_mul_f32_e32 v5, v5, v24
	v_mul_f32_e32 v6, v6, v25
	v_cvt_pk_bf16_f32 v210, v3, v4
	v_cvt_pk_bf16_f32 v211, v5, v6
	global_store_dwordx2 v53, v[210:211], s[48:49]
	v_lshlrev_b32_e32 v3, 16, v168
	v_and_b32_e32 v7, s71, v168
	v_lshlrev_b32_e32 v4, 16, v169
	v_and_b32_e32 v8, s71, v169
	v_lshlrev_b32_e32 v5, 16, v170
	v_and_b32_e32 v9, s71, v170
	v_lshlrev_b32_e32 v6, 16, v171
	v_and_b32_e32 v10, s71, v171
	v_sub_f32_e32 v3, 1.0, v3
	v_sub_f32_e32 v4, 1.0, v4
	v_sub_f32_e32 v5, 1.0, v5
	v_sub_f32_e32 v6, 1.0, v6
	v_fma_f32 v22, v3, v22, v7
	v_fma_f32 v23, v4, v23, v8
	v_fma_f32 v24, v5, v24, v9
	v_fma_f32 v25, v6, v25, v10
	v_lshlrev_b32_e32 v3, 16, v212
	v_and_b32_e32 v4, s71, v212
	v_lshlrev_b32_e32 v5, 16, v213
	v_and_b32_e32 v6, s71, v213
	v_mul_f32_e32 v3, v3, v22
	v_mul_f32_e32 v4, v4, v23
	v_mul_f32_e32 v5, v5, v24
	v_mul_f32_e32 v6, v6, v25
	v_cvt_pk_bf16_f32 v212, v3, v4
	v_cvt_pk_bf16_f32 v213, v5, v6
	global_store_dwordx2 v54, v[212:213], s[48:49]
	v_lshlrev_b32_e32 v3, 16, v180
	v_and_b32_e32 v7, s71, v180
	v_lshlrev_b32_e32 v4, 16, v181
	v_and_b32_e32 v8, s71, v181
	v_lshlrev_b32_e32 v5, 16, v182
	v_and_b32_e32 v9, s71, v182
	v_lshlrev_b32_e32 v6, 16, v183
	v_and_b32_e32 v10, s71, v183
	v_sub_f32_e32 v3, 1.0, v3
	v_sub_f32_e32 v4, 1.0, v4
	v_sub_f32_e32 v5, 1.0, v5
	v_sub_f32_e32 v6, 1.0, v6
	v_fma_f32 v22, v3, v22, v7
	v_fma_f32 v23, v4, v23, v8
	v_fma_f32 v24, v5, v24, v9
	v_fma_f32 v25, v6, v25, v10
	v_lshlrev_b32_e32 v3, 16, v214
	v_and_b32_e32 v4, s71, v214
	v_lshlrev_b32_e32 v5, 16, v215
	v_and_b32_e32 v6, s71, v215
	v_mul_f32_e32 v3, v3, v22
	v_mul_f32_e32 v4, v4, v23
	v_mul_f32_e32 v5, v5, v24
	v_mul_f32_e32 v6, v6, v25
	v_cvt_pk_bf16_f32 v214, v3, v4
	v_cvt_pk_bf16_f32 v215, v5, v6
	global_store_dwordx2 v55, v[214:215], s[48:49]
	s_add_u32 s48, s48, 0x5000
	s_addc_u32 s49, s49, 0
	s_cmp_eq_u32 s22, 0
	s_cbranch_scc1 .Llapp_done
	global_store_dwordx4 v1, v[22:25], s[92:93]
